# v4
# speedup vs baseline: 1.0223x; 1.0223x over previous
.LBB0_698:
	s_add_u32 s28, s26, 0xfffc0080
	s_addc_u32 s29, s27, -1
	s_add_i32 s68, 0, 0x10000
	v_add_u32_e32 v155, s68, v153
	ds_read_b128 v[138:141], v155
	ds_read_b128 v[142:145], v155 offset:1024
	ds_read_b128 v[146:149], v155 offset:2048
	ds_read_b128 v[156:159], v155 offset:3072
	s_cmp_eq_u32 s51, 12
	s_cselect_b32 s31, s21, s29
	s_cselect_b32 s30, s38, s28
	s_cselect_b32 s29, s7, s50
	s_cselect_b32 s28, s39, s46
	v_lshl_add_u64 v[192:193], s[26:27], 0, v[134:135]
	s_add_i32 m0, s58, 0xc000
	ds_read_b128 v[160:163], v154
	ds_read_b128 v[164:167], v154 offset:1024
	ds_read_b128 v[168:171], v154 offset:2048
	ds_read_b128 v[172:175], v154 offset:3072
	ds_read_b128 v[176:179], v154 offset:4096
	ds_read_b128 v[180:183], v154 offset:5120
	ds_read_b128 v[184:187], v154 offset:6144
	ds_read_b128 v[188:191], v154 offset:7168
	global_load_lds_dwordx4 v[192:193], off
	v_lshl_add_u64 v[192:193], s[26:27], 0, v[136:137]
	s_add_i32 m0, s58, 0xe000
	s_nop 0
	global_load_lds_dwordx4 v[192:193], off
	s_waitcnt lgkmcnt(8)
	s_barrier
	s_waitcnt lgkmcnt(0)
	s_setprio 1
	s_waitcnt lgkmcnt(0)
	v_mfma_f32_16x16x32_bf16 v[124:127], v[138:141], v[160:163], v[124:127]
	v_mfma_f32_16x16x32_bf16 v[120:123], v[146:149], v[160:163], v[120:123]
	v_mfma_f32_16x16x32_bf16 v[108:111], v[138:141], v[168:171], v[108:111]
	v_mfma_f32_16x16x32_bf16 v[104:107], v[146:149], v[168:171], v[104:107]
	v_mfma_f32_16x16x32_bf16 v[92:95], v[138:141], v[176:179], v[92:95]
	v_mfma_f32_16x16x32_bf16 v[88:91], v[146:149], v[176:179], v[88:91]
	v_mfma_f32_16x16x32_bf16 v[76:79], v[138:141], v[184:187], v[76:79]
	v_mfma_f32_16x16x32_bf16 v[72:75], v[146:149], v[184:187], v[72:75]
	v_mfma_f32_16x16x32_bf16 v[124:127], v[142:145], v[164:167], v[124:127]
	v_mfma_f32_16x16x32_bf16 v[120:123], v[156:159], v[164:167], v[120:123]
	v_mfma_f32_16x16x32_bf16 v[108:111], v[142:145], v[172:175], v[108:111]
	v_mfma_f32_16x16x32_bf16 v[104:107], v[156:159], v[172:175], v[104:107]
	v_mfma_f32_16x16x32_bf16 v[92:95], v[142:145], v[180:183], v[92:95]
	v_mfma_f32_16x16x32_bf16 v[88:91], v[156:159], v[180:183], v[88:91]
	v_mfma_f32_16x16x32_bf16 v[76:79], v[142:145], v[188:191], v[76:79]
	v_mfma_f32_16x16x32_bf16 v[72:75], v[156:159], v[188:191], v[72:75]
	s_setprio 0
	s_barrier
	s_add_i32 s70, 0, 0x14000
	s_add_i32 s68, s68, s57
	v_add_u32_e32 v155, s70, v153
	v_lshl_add_u64 v[210:211], s[28:29], 0, v[208:209]
	s_mov_b32 m0, s68
	ds_read_b128 v[192:195], v155
	ds_read_b128 v[196:199], v155 offset:1024
	ds_read_b128 v[200:203], v155 offset:2048
	ds_read_b128 v[204:207], v155 offset:3072
	global_load_lds_dwordx4 v[210:211], off
	v_lshl_add_u64 v[214:215], s[28:29], 0, v[128:129]
	s_add_i32 m0, s68, 0x2000
	s_nop 0
	global_load_lds_dwordx4 v[214:215], off
	s_barrier
	s_waitcnt lgkmcnt(0)
	s_setprio 1
	s_waitcnt lgkmcnt(0)
	v_mfma_f32_16x16x32_bf16 v[116:119], v[192:195], v[160:163], v[116:119]
	v_mfma_f32_16x16x32_bf16 v[112:115], v[200:203], v[160:163], v[112:115]
	v_mfma_f32_16x16x32_bf16 v[100:103], v[192:195], v[168:171], v[100:103]
	v_mfma_f32_16x16x32_bf16 v[96:99], v[200:203], v[168:171], v[96:99]
	v_mfma_f32_16x16x32_bf16 v[84:87], v[192:195], v[176:179], v[84:87]
	v_mfma_f32_16x16x32_bf16 v[80:83], v[200:203], v[176:179], v[80:83]
	v_mfma_f32_16x16x32_bf16 v[68:71], v[192:195], v[184:187], v[68:71]
	v_mfma_f32_16x16x32_bf16 v[64:67], v[200:203], v[184:187], v[64:67]
	v_mfma_f32_16x16x32_bf16 v[116:119], v[196:199], v[164:167], v[116:119]
	v_mfma_f32_16x16x32_bf16 v[112:115], v[204:207], v[164:167], v[112:115]
	v_mfma_f32_16x16x32_bf16 v[100:103], v[196:199], v[172:175], v[100:103]
	v_mfma_f32_16x16x32_bf16 v[96:99], v[204:207], v[172:175], v[96:99]
	v_mfma_f32_16x16x32_bf16 v[84:87], v[196:199], v[180:183], v[84:87]
	v_mfma_f32_16x16x32_bf16 v[80:83], v[204:207], v[180:183], v[80:83]
	v_mfma_f32_16x16x32_bf16 v[68:71], v[196:199], v[188:191], v[68:71]
	v_mfma_f32_16x16x32_bf16 v[64:67], v[204:207], v[188:191], v[64:67]
	s_setprio 0
	s_mov_b32 m0, s58
	v_lshl_add_u64 v[216:217], s[30:31], 0, v[132:133]
	s_barrier
	ds_read_b128 v[160:163], v154 offset:16384
	ds_read_b128 v[164:167], v154 offset:17408
	ds_read_b128 v[168:171], v154 offset:18432
	ds_read_b128 v[172:175], v154 offset:19456
	ds_read_b128 v[176:179], v154 offset:20480
	ds_read_b128 v[180:183], v154 offset:21504
	ds_read_b128 v[184:187], v154 offset:22528
	ds_read_b128 v[188:191], v154 offset:23552
	global_load_lds_dwordx4 v[216:217], off
	v_lshl_add_u64 v[218:219], s[30:31], 0, v[130:131]
	s_mov_b32 m0, s59
	s_nop 0
	global_load_lds_dwordx4 v[218:219], off
	s_barrier
	s_waitcnt lgkmcnt(0)
	s_setprio 1
	s_waitcnt lgkmcnt(0)
	v_mfma_f32_16x16x32_bf16 v[60:63], v[138:141], v[160:163], v[60:63]
	v_mfma_f32_16x16x32_bf16 v[56:59], v[146:149], v[160:163], v[56:59]
	v_mfma_f32_16x16x32_bf16 v[44:47], v[138:141], v[168:171], v[44:47]
	v_mfma_f32_16x16x32_bf16 v[40:43], v[146:149], v[168:171], v[40:43]
	v_mfma_f32_16x16x32_bf16 v[28:31], v[138:141], v[176:179], v[28:31]
	v_mfma_f32_16x16x32_bf16 v[24:27], v[146:149], v[176:179], v[24:27]
	v_mfma_f32_16x16x32_bf16 v[12:15], v[138:141], v[184:187], v[12:15]
	v_mfma_f32_16x16x32_bf16 v[8:11], v[146:149], v[184:187], v[8:11]
	v_mfma_f32_16x16x32_bf16 v[60:63], v[142:145], v[164:167], v[60:63]
	v_mfma_f32_16x16x32_bf16 v[56:59], v[156:159], v[164:167], v[56:59]
	v_mfma_f32_16x16x32_bf16 v[44:47], v[142:145], v[172:175], v[44:47]
	v_mfma_f32_16x16x32_bf16 v[40:43], v[156:159], v[172:175], v[40:43]
	v_mfma_f32_16x16x32_bf16 v[28:31], v[142:145], v[180:183], v[28:31]
	v_mfma_f32_16x16x32_bf16 v[24:27], v[156:159], v[180:183], v[24:27]
	v_mfma_f32_16x16x32_bf16 v[12:15], v[142:145], v[188:191], v[12:15]
	v_mfma_f32_16x16x32_bf16 v[8:11], v[156:159], v[188:191], v[8:11]
	s_setprio 0
	s_barrier
	s_add_u32 s68, s28, 0x40000
	s_addc_u32 s69, s29, 0
	s_add_i32 s70, s70, s57
	v_lshl_add_u64 v[138:139], s[68:69], 0, v[208:209]
	s_mov_b32 m0, s70
	s_nop 0
	global_load_lds_dwordx4 v[138:139], off
	v_lshl_add_u64 v[138:139], s[68:69], 0, v[128:129]
	s_add_i32 m0, s70, 0x2000
	s_nop 0
	global_load_lds_dwordx4 v[138:139], off
	s_waitcnt vmcnt(6)
	s_barrier
	s_setprio 1
	v_mfma_f32_16x16x32_bf16 v[52:55], v[192:195], v[160:163], v[52:55]
	v_mfma_f32_16x16x32_bf16 v[48:51], v[200:203], v[160:163], v[48:51]
	v_mfma_f32_16x16x32_bf16 v[36:39], v[192:195], v[168:171], v[36:39]
	v_mfma_f32_16x16x32_bf16 v[32:35], v[200:203], v[168:171], v[32:35]
	v_mfma_f32_16x16x32_bf16 v[20:23], v[192:195], v[176:179], v[20:23]
	v_mfma_f32_16x16x32_bf16 v[16:19], v[200:203], v[176:179], v[16:19]
	v_mfma_f32_16x16x32_bf16 v[4:7], v[192:195], v[184:187], v[4:7]
	v_mfma_f32_16x16x32_bf16 v[0:3], v[200:203], v[184:187], v[0:3]
	v_mfma_f32_16x16x32_bf16 v[52:55], v[196:199], v[164:167], v[52:55]
	v_mfma_f32_16x16x32_bf16 v[48:51], v[204:207], v[164:167], v[48:51]
	v_mfma_f32_16x16x32_bf16 v[36:39], v[196:199], v[172:175], v[36:39]
	v_mfma_f32_16x16x32_bf16 v[32:35], v[204:207], v[172:175], v[32:35]
	v_mfma_f32_16x16x32_bf16 v[20:23], v[196:199], v[180:183], v[20:23]
	v_mfma_f32_16x16x32_bf16 v[16:19], v[204:207], v[180:183], v[16:19]
	v_mfma_f32_16x16x32_bf16 v[4:7], v[196:199], v[188:191], v[4:7]
	v_mfma_f32_16x16x32_bf16 v[0:3], v[204:207], v[188:191], v[0:3]
	s_setprio 0
	s_add_i32 s68, 0, 0x18000
	v_add_u32_e32 v155, s68, v153
	s_barrier
	ds_read_b128 v[138:141], v155
	ds_read_b128 v[142:145], v155 offset:1024
	ds_read_b128 v[146:149], v155 offset:2048
	ds_read_b128 v[156:159], v155 offset:3072
	s_add_u32 s30, s30, 0x40000
	s_addc_u32 s31, s31, 0
	s_mov_b32 m0, s60
	v_lshl_add_u64 v[192:193], s[30:31], 0, v[132:133]
	ds_read_b128 v[160:163], v154 offset:32768
	ds_read_b128 v[164:167], v154 offset:33792
	ds_read_b128 v[168:171], v154 offset:34816
	ds_read_b128 v[172:175], v154 offset:35840
	ds_read_b128 v[176:179], v154 offset:36864
	ds_read_b128 v[180:183], v154 offset:37888
	ds_read_b128 v[184:187], v154 offset:38912
	ds_read_b128 v[188:191], v154 offset:39936
	global_load_lds_dwordx4 v[192:193], off
	v_lshl_add_u64 v[192:193], s[30:31], 0, v[130:131]
	s_mov_b32 m0, s61
	s_nop 0
	global_load_lds_dwordx4 v[192:193], off
	s_waitcnt lgkmcnt(8)
	s_barrier
	s_waitcnt lgkmcnt(0)
	s_setprio 1
	s_waitcnt lgkmcnt(0)
	v_mfma_f32_16x16x32_bf16 v[124:127], v[138:141], v[160:163], v[124:127]
	v_mfma_f32_16x16x32_bf16 v[120:123], v[146:149], v[160:163], v[120:123]
	v_mfma_f32_16x16x32_bf16 v[108:111], v[138:141], v[168:171], v[108:111]
	v_mfma_f32_16x16x32_bf16 v[104:107], v[146:149], v[168:171], v[104:107]
	v_mfma_f32_16x16x32_bf16 v[92:95], v[138:141], v[176:179], v[92:95]
	v_mfma_f32_16x16x32_bf16 v[88:91], v[146:149], v[176:179], v[88:91]
	v_mfma_f32_16x16x32_bf16 v[76:79], v[138:141], v[184:187], v[76:79]
	v_mfma_f32_16x16x32_bf16 v[72:75], v[146:149], v[184:187], v[72:75]
	v_mfma_f32_16x16x32_bf16 v[124:127], v[142:145], v[164:167], v[124:127]
	v_mfma_f32_16x16x32_bf16 v[120:123], v[156:159], v[164:167], v[120:123]
	v_mfma_f32_16x16x32_bf16 v[108:111], v[142:145], v[172:175], v[108:111]
	v_mfma_f32_16x16x32_bf16 v[104:107], v[156:159], v[172:175], v[104:107]
	v_mfma_f32_16x16x32_bf16 v[92:95], v[142:145], v[180:183], v[92:95]
	v_mfma_f32_16x16x32_bf16 v[88:91], v[156:159], v[180:183], v[88:91]
	v_mfma_f32_16x16x32_bf16 v[76:79], v[142:145], v[188:191], v[76:79]
	v_mfma_f32_16x16x32_bf16 v[72:75], v[156:159], v[188:191], v[72:75]
	s_setprio 0
	s_barrier
	s_add_i32 s30, 0, 0x1c000
	s_add_i32 s31, s68, s57
	v_add_u32_e32 v155, s30, v153
	v_lshl_add_u64 v[210:211], v[210:211], 0, s[40:41]
	s_mov_b32 m0, s31
	ds_read_b128 v[192:195], v155
	ds_read_b128 v[196:199], v155 offset:1024
	ds_read_b128 v[200:203], v155 offset:2048
	ds_read_b128 v[204:207], v155 offset:3072
	global_load_lds_dwordx4 v[210:211], off
	v_lshl_add_u64 v[210:211], v[214:215], 0, s[40:41]
	s_add_i32 m0, s31, 0x2000
	s_nop 0
	global_load_lds_dwordx4 v[210:211], off
	s_barrier
	s_waitcnt lgkmcnt(0)
	s_setprio 1
	s_waitcnt lgkmcnt(0)
	v_mfma_f32_16x16x32_bf16 v[116:119], v[192:195], v[160:163], v[116:119]
	v_mfma_f32_16x16x32_bf16 v[112:115], v[200:203], v[160:163], v[112:115]
	v_mfma_f32_16x16x32_bf16 v[100:103], v[192:195], v[168:171], v[100:103]
	v_mfma_f32_16x16x32_bf16 v[96:99], v[200:203], v[168:171], v[96:99]
	v_mfma_f32_16x16x32_bf16 v[84:87], v[192:195], v[176:179], v[84:87]
	v_mfma_f32_16x16x32_bf16 v[80:83], v[200:203], v[176:179], v[80:83]
	v_mfma_f32_16x16x32_bf16 v[68:71], v[192:195], v[184:187], v[68:71]
	v_mfma_f32_16x16x32_bf16 v[64:67], v[200:203], v[184:187], v[64:67]
	v_mfma_f32_16x16x32_bf16 v[116:119], v[196:199], v[164:167], v[116:119]
	v_mfma_f32_16x16x32_bf16 v[112:115], v[204:207], v[164:167], v[112:115]
	v_mfma_f32_16x16x32_bf16 v[100:103], v[196:199], v[172:175], v[100:103]
	v_mfma_f32_16x16x32_bf16 v[96:99], v[204:207], v[172:175], v[96:99]
	v_mfma_f32_16x16x32_bf16 v[84:87], v[196:199], v[180:183], v[84:87]
	v_mfma_f32_16x16x32_bf16 v[80:83], v[204:207], v[180:183], v[80:83]
	v_mfma_f32_16x16x32_bf16 v[68:71], v[196:199], v[188:191], v[68:71]
	v_mfma_f32_16x16x32_bf16 v[64:67], v[204:207], v[188:191], v[64:67]
	s_setprio 0
	s_mov_b32 m0, s64
	v_lshl_add_u64 v[210:211], v[216:217], 0, s[40:41]
	s_barrier
	ds_read_b128 v[160:163], v154 offset:49152
	ds_read_b128 v[164:167], v154 offset:50176
	ds_read_b128 v[168:171], v154 offset:51200
	ds_read_b128 v[172:175], v154 offset:52224
	ds_read_b128 v[176:179], v154 offset:53248
	ds_read_b128 v[180:183], v154 offset:54272
	ds_read_b128 v[184:187], v154 offset:55296
	ds_read_b128 v[188:191], v154 offset:56320
	global_load_lds_dwordx4 v[210:211], off
	v_lshl_add_u64 v[210:211], v[218:219], 0, s[40:41]
	s_mov_b32 m0, s65
	s_nop 0
	global_load_lds_dwordx4 v[210:211], off
	s_barrier
	s_waitcnt lgkmcnt(0)
	s_setprio 1
	s_waitcnt lgkmcnt(0)
	v_mfma_f32_16x16x32_bf16 v[60:63], v[138:141], v[160:163], v[60:63]
	v_mfma_f32_16x16x32_bf16 v[56:59], v[146:149], v[160:163], v[56:59]
	v_mfma_f32_16x16x32_bf16 v[44:47], v[138:141], v[168:171], v[44:47]
	v_mfma_f32_16x16x32_bf16 v[40:43], v[146:149], v[168:171], v[40:43]
	v_mfma_f32_16x16x32_bf16 v[28:31], v[138:141], v[176:179], v[28:31]
	v_mfma_f32_16x16x32_bf16 v[24:27], v[146:149], v[176:179], v[24:27]
	v_mfma_f32_16x16x32_bf16 v[12:15], v[138:141], v[184:187], v[12:15]
	v_mfma_f32_16x16x32_bf16 v[8:11], v[146:149], v[184:187], v[8:11]
	v_mfma_f32_16x16x32_bf16 v[60:63], v[142:145], v[164:167], v[60:63]
	v_mfma_f32_16x16x32_bf16 v[56:59], v[156:159], v[164:167], v[56:59]
	v_mfma_f32_16x16x32_bf16 v[44:47], v[142:145], v[172:175], v[44:47]
	v_mfma_f32_16x16x32_bf16 v[40:43], v[156:159], v[172:175], v[40:43]
	v_mfma_f32_16x16x32_bf16 v[28:31], v[142:145], v[180:183], v[28:31]
	v_mfma_f32_16x16x32_bf16 v[24:27], v[156:159], v[180:183], v[24:27]
	v_mfma_f32_16x16x32_bf16 v[12:15], v[142:145], v[188:191], v[12:15]
	v_mfma_f32_16x16x32_bf16 v[8:11], v[156:159], v[188:191], v[8:11]
	s_setprio 0
	s_barrier
	s_add_u32 s28, s28, 0x40080
	s_addc_u32 s29, s29, 0
	s_add_i32 s30, s30, s57
	v_lshl_add_u64 v[138:139], s[28:29], 0, v[208:209]
	s_mov_b32 m0, s30
	s_nop 0
	global_load_lds_dwordx4 v[138:139], off
	v_lshl_add_u64 v[138:139], s[28:29], 0, v[128:129]
	s_add_i32 m0, s30, 0x2000
	s_nop 0
	global_load_lds_dwordx4 v[138:139], off
	s_waitcnt vmcnt(6)
	s_barrier
	s_setprio 1
	v_mfma_f32_16x16x32_bf16 v[52:55], v[192:195], v[160:163], v[52:55]
	v_mfma_f32_16x16x32_bf16 v[48:51], v[200:203], v[160:163], v[48:51]
	v_mfma_f32_16x16x32_bf16 v[36:39], v[192:195], v[168:171], v[36:39]
	v_mfma_f32_16x16x32_bf16 v[32:35], v[200:203], v[168:171], v[32:35]
	v_mfma_f32_16x16x32_bf16 v[20:23], v[192:195], v[176:179], v[20:23]
	v_mfma_f32_16x16x32_bf16 v[16:19], v[200:203], v[176:179], v[16:19]
	v_mfma_f32_16x16x32_bf16 v[4:7], v[192:195], v[184:187], v[4:7]
	v_mfma_f32_16x16x32_bf16 v[0:3], v[200:203], v[184:187], v[0:3]
	v_mfma_f32_16x16x32_bf16 v[52:55], v[196:199], v[164:167], v[52:55]
	v_mfma_f32_16x16x32_bf16 v[48:51], v[204:207], v[164:167], v[48:51]
	v_mfma_f32_16x16x32_bf16 v[36:39], v[196:199], v[172:175], v[36:39]
	v_mfma_f32_16x16x32_bf16 v[32:35], v[204:207], v[172:175], v[32:35]
	v_mfma_f32_16x16x32_bf16 v[20:23], v[196:199], v[180:183], v[20:23]
	v_mfma_f32_16x16x32_bf16 v[16:19], v[204:207], v[180:183], v[16:19]
	v_mfma_f32_16x16x32_bf16 v[4:7], v[196:199], v[188:191], v[4:7]
	v_mfma_f32_16x16x32_bf16 v[0:3], v[204:207], v[188:191], v[0:3]
	s_setprio 0
	s_add_i32 s51, s51, 2
	s_add_u32 s26, s26, 0x100
	s_addc_u32 s27, s27, 0
	s_add_u32 s46, s46, 0x100
	s_addc_u32 s50, s50, 0
	s_cmp_gt_u32 s51, 13
	s_barrier
	s_cbranch_scc0 .LBB0_698
	s_cmp_lt_i32 s34, 4
	s_cselect_b64 vcc, -1, 0
	v_mov_b32_e32 v138, 0x3e38aa3b
	s_nop 0
	v_cndmask_b32_e32 v155, 1.0, v138, vcc
	s_and_b64 s[26:27], vcc, exec
	v_lshl_add_u32 v140, s35, 8, v152
	s_cselect_b32 s7, s9, s11
	s_cselect_b32 s21, s8, s10
	v_mov_b32_e32 v138, s21
	v_mov_b32_e32 v139, s7
	v_lshlrev_b32_e32 v142, 3, v151
	v_mov_b32_e32 v143, 0
	v_lshl_add_u64 v[138:139], v[142:143], 2, v[138:139]
	global_load_dwordx4 v[188:191], v[138:139], off
	global_load_dwordx4 v[192:195], v[138:139], off offset:16
	global_load_dwordx4 v[196:199], v[138:139], off offset:128
	global_load_dwordx4 v[200:203], v[138:139], off offset:144
	s_lshl_b32 s7, s34, 8
	s_or_b32 s26, s7, s66
	s_ashr_i32 s27, s26, 31
	s_lshl_b64 s[26:27], s[26:27], 1
	s_add_u32 s26, s62, s26
	s_addc_u32 s27, s63, s27
	s_mov_b32 s34, s6
	s_mov_b32 s35, s20
	s_mov_b64 s[28:29], s[24:25]
	v_mbcnt_lo_u32_b32 v210, -1, 0
	v_mbcnt_hi_u32_b32 v210, -1, v210
	v_and_b32_e32 v210, 48, v210
	v_lshl_add_u32 v210, v140, 6, v210
	v_lshlrev_b32_e32 v211, 12, v140
	v_lshl_add_u32 v211, v151, 4, v211
	global_load_dwordx4 v[156:159], v210, s[18:19]
	global_load_dwordx4 v[160:163], v210, s[18:19] offset:1024
	global_load_dwordx4 v[164:167], v210, s[18:19] offset:2048
	global_load_dwordx4 v[168:171], v210, s[18:19] offset:3072
	v_add_u32_e32 v210, 0x2000, v210
	global_load_dwordx4 v[172:175], v210, s[18:19]
	global_load_dwordx4 v[176:179], v210, s[18:19] offset:1024
	global_load_dwordx4 v[180:183], v210, s[18:19] offset:2048
	global_load_dwordx4 v[184:187], v210, s[18:19] offset:3072
	s_waitcnt vmcnt(7)
	v_pk_add_f32 v[156:157], v[156:157], v[158:159]
	s_nop 0
	v_add_f32_e32 v214, v156, v157
	v_mov_b32_e32 v215, v214
	s_nop 1
	v_permlane16_swap_b32_e32 v214, v215
	s_nop 0
	v_add_f32_e32 v214, v214, v215
	v_mov_b32_e32 v215, v214
	s_nop 1
	v_permlane32_swap_b32_e32 v214, v215
	s_nop 0
	v_add_f32_e32 v214, v214, v215
	v_fmamk_f32 v214, v214, 0x3a800000, v248
	v_rsq_f32_e32 v216, v214
	s_nop 0
	v_pk_mul_f32 v[124:125], v[124:125], v[216:217] op_sel_hi:[1,0]
	v_pk_mul_f32 v[126:127], v[126:127], v[216:217] op_sel_hi:[1,0]
	v_pk_mul_f32 v[120:121], v[120:121], v[216:217] op_sel_hi:[1,0]
	v_pk_mul_f32 v[122:123], v[122:123], v[216:217] op_sel_hi:[1,0]
	v_pk_mul_f32 v[116:117], v[116:117], v[216:217] op_sel_hi:[1,0]
	v_pk_mul_f32 v[118:119], v[118:119], v[216:217] op_sel_hi:[1,0]
	v_pk_mul_f32 v[112:113], v[112:113], v[216:217] op_sel_hi:[1,0]
	v_pk_mul_f32 v[114:115], v[114:115], v[216:217] op_sel_hi:[1,0]
	v_pk_mul_f32 v[148:149], v[124:125], v[124:125]
	v_pk_fma_f32 v[148:149], v[126:127], v[126:127], v[148:149]
	v_pk_fma_f32 v[148:149], v[120:121], v[120:121], v[148:149]
	v_pk_fma_f32 v[148:149], v[122:123], v[122:123], v[148:149]
	v_pk_fma_f32 v[148:149], v[116:117], v[116:117], v[148:149]
	v_pk_fma_f32 v[148:149], v[118:119], v[118:119], v[148:149]
	v_pk_fma_f32 v[148:149], v[112:113], v[112:113], v[148:149]
	v_pk_fma_f32 v[148:149], v[114:115], v[114:115], v[148:149]
	v_add_f32_e32 v214, v148, v149
	v_mov_b32_e32 v215, v214
	s_nop 1
	v_permlane16_swap_b32_e32 v214, v215
	s_nop 0
	v_add_f32_e32 v214, v214, v215
	v_mov_b32_e32 v215, v214
	s_nop 1
	v_permlane32_swap_b32_e32 v214, v215
	s_nop 0
	v_add_f32_e32 v214, v214, v215
	v_fmamk_f32 v214, v214, 0x3c800000, v248
	v_rsq_f32_e32 v214, v214
	s_nop 0
	v_mul_f32_e32 v218, v155, v214
	v_pk_mul_f32 v[156:157], v[188:189], v[218:219] op_sel_hi:[1,0]
	v_pk_mul_f32 v[124:125], v[124:125], v[156:157]
	v_pk_mul_f32 v[156:157], v[190:191], v[218:219] op_sel_hi:[1,0]
	v_pk_mul_f32 v[126:127], v[126:127], v[156:157]
	v_pk_mul_f32 v[156:157], v[192:193], v[218:219] op_sel_hi:[1,0]
	v_pk_mul_f32 v[120:121], v[120:121], v[156:157]
	v_pk_mul_f32 v[156:157], v[194:195], v[218:219] op_sel_hi:[1,0]
	v_pk_mul_f32 v[122:123], v[122:123], v[156:157]
	v_cvt_pk_bf16_f32 v204, v124, v125
	v_cvt_pk_bf16_f32 v205, v126, v127
	v_cvt_pk_bf16_f32 v206, v120, v121
	v_cvt_pk_bf16_f32 v207, v122, v123
	global_store_dwordx4 v211, v[204:207], s[26:27]
	v_pk_mul_f32 v[156:157], v[196:197], v[218:219] op_sel_hi:[1,0]
	v_pk_mul_f32 v[116:117], v[116:117], v[156:157]
	v_pk_mul_f32 v[156:157], v[198:199], v[218:219] op_sel_hi:[1,0]
	v_pk_mul_f32 v[118:119], v[118:119], v[156:157]
	v_pk_mul_f32 v[156:157], v[200:201], v[218:219] op_sel_hi:[1,0]
	v_pk_mul_f32 v[112:113], v[112:113], v[156:157]
	v_pk_mul_f32 v[156:157], v[202:203], v[218:219] op_sel_hi:[1,0]
	v_pk_mul_f32 v[114:115], v[114:115], v[156:157]
	v_cvt_pk_bf16_f32 v144, v116, v117
	v_cvt_pk_bf16_f32 v145, v118, v119
	v_cvt_pk_bf16_f32 v146, v112, v113
	v_cvt_pk_bf16_f32 v147, v114, v115
	global_store_dwordx4 v211, v[144:147], s[26:27] offset:64
	v_add_u32_e32 v211, 0x10000, v211
	s_waitcnt vmcnt(8)
	v_pk_add_f32 v[160:161], v[160:161], v[162:163]
	s_nop 0
	v_add_f32_e32 v214, v160, v161
	v_mov_b32_e32 v215, v214
	s_nop 1
	v_permlane16_swap_b32_e32 v214, v215
	s_nop 0
	v_add_f32_e32 v214, v214, v215
	v_mov_b32_e32 v215, v214
	s_nop 1
	v_permlane32_swap_b32_e32 v214, v215
	s_nop 0
	v_add_f32_e32 v214, v214, v215
	v_fmamk_f32 v214, v214, 0x3a800000, v248
	v_rsq_f32_e32 v216, v214
	s_nop 0
	v_pk_mul_f32 v[108:109], v[108:109], v[216:217] op_sel_hi:[1,0]
	v_pk_mul_f32 v[110:111], v[110:111], v[216:217] op_sel_hi:[1,0]
	v_pk_mul_f32 v[104:105], v[104:105], v[216:217] op_sel_hi:[1,0]
	v_pk_mul_f32 v[106:107], v[106:107], v[216:217] op_sel_hi:[1,0]
	v_pk_mul_f32 v[100:101], v[100:101], v[216:217] op_sel_hi:[1,0]
	v_pk_mul_f32 v[102:103], v[102:103], v[216:217] op_sel_hi:[1,0]
	v_pk_mul_f32 v[96:97], v[96:97], v[216:217] op_sel_hi:[1,0]
	v_pk_mul_f32 v[98:99], v[98:99], v[216:217] op_sel_hi:[1,0]
	v_pk_mul_f32 v[148:149], v[108:109], v[108:109]
	v_pk_fma_f32 v[148:149], v[110:111], v[110:111], v[148:149]
	v_pk_fma_f32 v[148:149], v[104:105], v[104:105], v[148:149]
	v_pk_fma_f32 v[148:149], v[106:107], v[106:107], v[148:149]
	v_pk_fma_f32 v[148:149], v[100:101], v[100:101], v[148:149]
	v_pk_fma_f32 v[148:149], v[102:103], v[102:103], v[148:149]
	v_pk_fma_f32 v[148:149], v[96:97], v[96:97], v[148:149]
	v_pk_fma_f32 v[148:149], v[98:99], v[98:99], v[148:149]
	v_add_f32_e32 v214, v148, v149
	v_mov_b32_e32 v215, v214
	s_nop 1
	v_permlane16_swap_b32_e32 v214, v215
	s_nop 0
	v_add_f32_e32 v214, v214, v215
	v_mov_b32_e32 v215, v214
	s_nop 1
	v_permlane32_swap_b32_e32 v214, v215
	s_nop 0
	v_add_f32_e32 v214, v214, v215
	v_fmamk_f32 v214, v214, 0x3c800000, v248
	v_rsq_f32_e32 v214, v214
	s_nop 0
	v_mul_f32_e32 v218, v155, v214
	v_pk_mul_f32 v[160:161], v[188:189], v[218:219] op_sel_hi:[1,0]
	v_pk_mul_f32 v[108:109], v[108:109], v[160:161]
	v_pk_mul_f32 v[160:161], v[190:191], v[218:219] op_sel_hi:[1,0]
	v_pk_mul_f32 v[110:111], v[110:111], v[160:161]
	v_pk_mul_f32 v[160:161], v[192:193], v[218:219] op_sel_hi:[1,0]
	v_pk_mul_f32 v[104:105], v[104:105], v[160:161]
	v_pk_mul_f32 v[160:161], v[194:195], v[218:219] op_sel_hi:[1,0]
	v_pk_mul_f32 v[106:107], v[106:107], v[160:161]
	v_cvt_pk_bf16_f32 v204, v108, v109
	v_cvt_pk_bf16_f32 v205, v110, v111
	v_cvt_pk_bf16_f32 v206, v104, v105
	v_cvt_pk_bf16_f32 v207, v106, v107
	global_store_dwordx4 v211, v[204:207], s[26:27]
	v_pk_mul_f32 v[160:161], v[196:197], v[218:219] op_sel_hi:[1,0]
	v_pk_mul_f32 v[100:101], v[100:101], v[160:161]
	v_pk_mul_f32 v[160:161], v[198:199], v[218:219] op_sel_hi:[1,0]
	v_pk_mul_f32 v[102:103], v[102:103], v[160:161]
	v_pk_mul_f32 v[160:161], v[200:201], v[218:219] op_sel_hi:[1,0]
	v_pk_mul_f32 v[96:97], v[96:97], v[160:161]
	v_pk_mul_f32 v[160:161], v[202:203], v[218:219] op_sel_hi:[1,0]
	v_pk_mul_f32 v[98:99], v[98:99], v[160:161]
	v_cvt_pk_bf16_f32 v144, v100, v101
	v_cvt_pk_bf16_f32 v145, v102, v103
	v_cvt_pk_bf16_f32 v146, v96, v97
	v_cvt_pk_bf16_f32 v147, v98, v99
	global_store_dwordx4 v211, v[144:147], s[26:27] offset:64
	v_add_u32_e32 v211, 0x10000, v211
	s_waitcnt vmcnt(9)
	v_pk_add_f32 v[164:165], v[164:165], v[166:167]
	s_nop 0
	v_add_f32_e32 v214, v164, v165
	v_mov_b32_e32 v215, v214
	s_nop 1
	v_permlane16_swap_b32_e32 v214, v215
	s_nop 0
	v_add_f32_e32 v214, v214, v215
	v_mov_b32_e32 v215, v214
	s_nop 1
	v_permlane32_swap_b32_e32 v214, v215
	s_nop 0
	v_add_f32_e32 v214, v214, v215
	v_fmamk_f32 v214, v214, 0x3a800000, v248
	v_rsq_f32_e32 v216, v214
	s_nop 0
	v_pk_mul_f32 v[92:93], v[92:93], v[216:217] op_sel_hi:[1,0]
	v_pk_mul_f32 v[94:95], v[94:95], v[216:217] op_sel_hi:[1,0]
	v_pk_mul_f32 v[88:89], v[88:89], v[216:217] op_sel_hi:[1,0]
	v_pk_mul_f32 v[90:91], v[90:91], v[216:217] op_sel_hi:[1,0]
	v_pk_mul_f32 v[84:85], v[84:85], v[216:217] op_sel_hi:[1,0]
	v_pk_mul_f32 v[86:87], v[86:87], v[216:217] op_sel_hi:[1,0]
	v_pk_mul_f32 v[80:81], v[80:81], v[216:217] op_sel_hi:[1,0]
	v_pk_mul_f32 v[82:83], v[82:83], v[216:217] op_sel_hi:[1,0]
	v_pk_mul_f32 v[148:149], v[92:93], v[92:93]
	v_pk_fma_f32 v[148:149], v[94:95], v[94:95], v[148:149]
	v_pk_fma_f32 v[148:149], v[88:89], v[88:89], v[148:149]
	v_pk_fma_f32 v[148:149], v[90:91], v[90:91], v[148:149]
	v_pk_fma_f32 v[148:149], v[84:85], v[84:85], v[148:149]
	v_pk_fma_f32 v[148:149], v[86:87], v[86:87], v[148:149]
	v_pk_fma_f32 v[148:149], v[80:81], v[80:81], v[148:149]
	v_pk_fma_f32 v[148:149], v[82:83], v[82:83], v[148:149]
	v_add_f32_e32 v214, v148, v149
	v_mov_b32_e32 v215, v214
	s_nop 1
	v_permlane16_swap_b32_e32 v214, v215
	s_nop 0
	v_add_f32_e32 v214, v214, v215
	v_mov_b32_e32 v215, v214
	s_nop 1
	v_permlane32_swap_b32_e32 v214, v215
	s_nop 0
	v_add_f32_e32 v214, v214, v215
	v_fmamk_f32 v214, v214, 0x3c800000, v248
	v_rsq_f32_e32 v214, v214
	s_nop 0
	v_mul_f32_e32 v218, v155, v214
	v_pk_mul_f32 v[164:165], v[188:189], v[218:219] op_sel_hi:[1,0]
	v_pk_mul_f32 v[92:93], v[92:93], v[164:165]
	v_pk_mul_f32 v[164:165], v[190:191], v[218:219] op_sel_hi:[1,0]
	v_pk_mul_f32 v[94:95], v[94:95], v[164:165]
	v_pk_mul_f32 v[164:165], v[192:193], v[218:219] op_sel_hi:[1,0]
	v_pk_mul_f32 v[88:89], v[88:89], v[164:165]
	v_pk_mul_f32 v[164:165], v[194:195], v[218:219] op_sel_hi:[1,0]
	v_pk_mul_f32 v[90:91], v[90:91], v[164:165]
	v_cvt_pk_bf16_f32 v204, v92, v93
	v_cvt_pk_bf16_f32 v205, v94, v95
	v_cvt_pk_bf16_f32 v206, v88, v89
	v_cvt_pk_bf16_f32 v207, v90, v91
	global_store_dwordx4 v211, v[204:207], s[26:27]
	v_pk_mul_f32 v[164:165], v[196:197], v[218:219] op_sel_hi:[1,0]
	v_pk_mul_f32 v[84:85], v[84:85], v[164:165]
	v_pk_mul_f32 v[164:165], v[198:199], v[218:219] op_sel_hi:[1,0]
	v_pk_mul_f32 v[86:87], v[86:87], v[164:165]
	v_pk_mul_f32 v[164:165], v[200:201], v[218:219] op_sel_hi:[1,0]
	v_pk_mul_f32 v[80:81], v[80:81], v[164:165]
	v_pk_mul_f32 v[164:165], v[202:203], v[218:219] op_sel_hi:[1,0]
	v_pk_mul_f32 v[82:83], v[82:83], v[164:165]
	v_cvt_pk_bf16_f32 v144, v84, v85
	v_cvt_pk_bf16_f32 v145, v86, v87
	v_cvt_pk_bf16_f32 v146, v80, v81
	v_cvt_pk_bf16_f32 v147, v82, v83
	global_store_dwordx4 v211, v[144:147], s[26:27] offset:64
	v_add_u32_e32 v211, 0x10000, v211
	s_waitcnt vmcnt(10)
	v_pk_add_f32 v[168:169], v[168:169], v[170:171]
	s_nop 0
	v_add_f32_e32 v214, v168, v169
	v_mov_b32_e32 v215, v214
	s_nop 1
	v_permlane16_swap_b32_e32 v214, v215
	s_nop 0
	v_add_f32_e32 v214, v214, v215
	v_mov_b32_e32 v215, v214
	s_nop 1
	v_permlane32_swap_b32_e32 v214, v215
	s_nop 0
	v_add_f32_e32 v214, v214, v215
	v_fmamk_f32 v214, v214, 0x3a800000, v248
	v_rsq_f32_e32 v216, v214
	s_nop 0
	v_pk_mul_f32 v[76:77], v[76:77], v[216:217] op_sel_hi:[1,0]
	v_pk_mul_f32 v[78:79], v[78:79], v[216:217] op_sel_hi:[1,0]
	v_pk_mul_f32 v[72:73], v[72:73], v[216:217] op_sel_hi:[1,0]
	v_pk_mul_f32 v[74:75], v[74:75], v[216:217] op_sel_hi:[1,0]
	v_pk_mul_f32 v[68:69], v[68:69], v[216:217] op_sel_hi:[1,0]
	v_pk_mul_f32 v[70:71], v[70:71], v[216:217] op_sel_hi:[1,0]
	v_pk_mul_f32 v[64:65], v[64:65], v[216:217] op_sel_hi:[1,0]
	v_pk_mul_f32 v[66:67], v[66:67], v[216:217] op_sel_hi:[1,0]
	v_pk_mul_f32 v[148:149], v[76:77], v[76:77]
	v_pk_fma_f32 v[148:149], v[78:79], v[78:79], v[148:149]
	v_pk_fma_f32 v[148:149], v[72:73], v[72:73], v[148:149]
	v_pk_fma_f32 v[148:149], v[74:75], v[74:75], v[148:149]
	v_pk_fma_f32 v[148:149], v[68:69], v[68:69], v[148:149]
	v_pk_fma_f32 v[148:149], v[70:71], v[70:71], v[148:149]
	v_pk_fma_f32 v[148:149], v[64:65], v[64:65], v[148:149]
	v_pk_fma_f32 v[148:149], v[66:67], v[66:67], v[148:149]
	v_add_f32_e32 v214, v148, v149
	v_mov_b32_e32 v215, v214
	s_nop 1
	v_permlane16_swap_b32_e32 v214, v215
	s_nop 0
	v_add_f32_e32 v214, v214, v215
	v_mov_b32_e32 v215, v214
	s_nop 1
	v_permlane32_swap_b32_e32 v214, v215
	s_nop 0
	v_add_f32_e32 v214, v214, v215
	v_fmamk_f32 v214, v214, 0x3c800000, v248
	v_rsq_f32_e32 v214, v214
	s_nop 0
	v_mul_f32_e32 v218, v155, v214
	v_pk_mul_f32 v[168:169], v[188:189], v[218:219] op_sel_hi:[1,0]
	v_pk_mul_f32 v[76:77], v[76:77], v[168:169]
	v_pk_mul_f32 v[168:169], v[190:191], v[218:219] op_sel_hi:[1,0]
	v_pk_mul_f32 v[78:79], v[78:79], v[168:169]
	v_pk_mul_f32 v[168:169], v[192:193], v[218:219] op_sel_hi:[1,0]
	v_pk_mul_f32 v[72:73], v[72:73], v[168:169]
	v_pk_mul_f32 v[168:169], v[194:195], v[218:219] op_sel_hi:[1,0]
	v_pk_mul_f32 v[74:75], v[74:75], v[168:169]
	v_cvt_pk_bf16_f32 v204, v76, v77
	v_cvt_pk_bf16_f32 v205, v78, v79
	v_cvt_pk_bf16_f32 v206, v72, v73
	v_cvt_pk_bf16_f32 v207, v74, v75
	global_store_dwordx4 v211, v[204:207], s[26:27]
	v_pk_mul_f32 v[168:169], v[196:197], v[218:219] op_sel_hi:[1,0]
	v_pk_mul_f32 v[68:69], v[68:69], v[168:169]
	v_pk_mul_f32 v[168:169], v[198:199], v[218:219] op_sel_hi:[1,0]
	v_pk_mul_f32 v[70:71], v[70:71], v[168:169]
	v_pk_mul_f32 v[168:169], v[200:201], v[218:219] op_sel_hi:[1,0]
	v_pk_mul_f32 v[64:65], v[64:65], v[168:169]
	v_pk_mul_f32 v[168:169], v[202:203], v[218:219] op_sel_hi:[1,0]
	v_pk_mul_f32 v[66:67], v[66:67], v[168:169]
	v_cvt_pk_bf16_f32 v144, v68, v69
	v_cvt_pk_bf16_f32 v145, v70, v71
	v_cvt_pk_bf16_f32 v146, v64, v65
	v_cvt_pk_bf16_f32 v147, v66, v67
	global_store_dwordx4 v211, v[144:147], s[26:27] offset:64
	v_add_u32_e32 v211, 0x50000, v211
	s_waitcnt vmcnt(11)
	v_pk_add_f32 v[172:173], v[172:173], v[174:175]
	s_nop 0
	v_add_f32_e32 v214, v172, v173
	v_mov_b32_e32 v215, v214
	s_nop 1
	v_permlane16_swap_b32_e32 v214, v215
	s_nop 0
	v_add_f32_e32 v214, v214, v215
	v_mov_b32_e32 v215, v214
	s_nop 1
	v_permlane32_swap_b32_e32 v214, v215
	s_nop 0
	v_add_f32_e32 v214, v214, v215
	v_fmamk_f32 v214, v214, 0x3a800000, v248
	v_rsq_f32_e32 v216, v214
	s_nop 0
	v_pk_mul_f32 v[60:61], v[60:61], v[216:217] op_sel_hi:[1,0]
	v_pk_mul_f32 v[62:63], v[62:63], v[216:217] op_sel_hi:[1,0]
	v_pk_mul_f32 v[56:57], v[56:57], v[216:217] op_sel_hi:[1,0]
	v_pk_mul_f32 v[58:59], v[58:59], v[216:217] op_sel_hi:[1,0]
	v_pk_mul_f32 v[52:53], v[52:53], v[216:217] op_sel_hi:[1,0]
	v_pk_mul_f32 v[54:55], v[54:55], v[216:217] op_sel_hi:[1,0]
	v_pk_mul_f32 v[48:49], v[48:49], v[216:217] op_sel_hi:[1,0]
	v_pk_mul_f32 v[50:51], v[50:51], v[216:217] op_sel_hi:[1,0]
	v_pk_mul_f32 v[148:149], v[60:61], v[60:61]
	v_pk_fma_f32 v[148:149], v[62:63], v[62:63], v[148:149]
	v_pk_fma_f32 v[148:149], v[56:57], v[56:57], v[148:149]
	v_pk_fma_f32 v[148:149], v[58:59], v[58:59], v[148:149]
	v_pk_fma_f32 v[148:149], v[52:53], v[52:53], v[148:149]
	v_pk_fma_f32 v[148:149], v[54:55], v[54:55], v[148:149]
	v_pk_fma_f32 v[148:149], v[48:49], v[48:49], v[148:149]
	v_pk_fma_f32 v[148:149], v[50:51], v[50:51], v[148:149]
	v_add_f32_e32 v214, v148, v149
	v_mov_b32_e32 v215, v214
	s_nop 1
	v_permlane16_swap_b32_e32 v214, v215
	s_nop 0
	v_add_f32_e32 v214, v214, v215
	v_mov_b32_e32 v215, v214
	s_nop 1
	v_permlane32_swap_b32_e32 v214, v215
	s_nop 0
	v_add_f32_e32 v214, v214, v215
	v_fmamk_f32 v214, v214, 0x3c800000, v248
	v_rsq_f32_e32 v214, v214
	s_nop 0
	v_mul_f32_e32 v218, v155, v214
	v_pk_mul_f32 v[172:173], v[188:189], v[218:219] op_sel_hi:[1,0]
	v_pk_mul_f32 v[60:61], v[60:61], v[172:173]
	v_pk_mul_f32 v[172:173], v[190:191], v[218:219] op_sel_hi:[1,0]
	v_pk_mul_f32 v[62:63], v[62:63], v[172:173]
	v_pk_mul_f32 v[172:173], v[192:193], v[218:219] op_sel_hi:[1,0]
	v_pk_mul_f32 v[56:57], v[56:57], v[172:173]
	v_pk_mul_f32 v[172:173], v[194:195], v[218:219] op_sel_hi:[1,0]
	v_pk_mul_f32 v[58:59], v[58:59], v[172:173]
	v_cvt_pk_bf16_f32 v204, v60, v61
	v_cvt_pk_bf16_f32 v205, v62, v63
	v_cvt_pk_bf16_f32 v206, v56, v57
	v_cvt_pk_bf16_f32 v207, v58, v59
	global_store_dwordx4 v211, v[204:207], s[26:27]
	v_pk_mul_f32 v[172:173], v[196:197], v[218:219] op_sel_hi:[1,0]
	v_pk_mul_f32 v[52:53], v[52:53], v[172:173]
	v_pk_mul_f32 v[172:173], v[198:199], v[218:219] op_sel_hi:[1,0]
	v_pk_mul_f32 v[54:55], v[54:55], v[172:173]
	v_pk_mul_f32 v[172:173], v[200:201], v[218:219] op_sel_hi:[1,0]
	v_pk_mul_f32 v[48:49], v[48:49], v[172:173]
	v_pk_mul_f32 v[172:173], v[202:203], v[218:219] op_sel_hi:[1,0]
	v_pk_mul_f32 v[50:51], v[50:51], v[172:173]
	v_cvt_pk_bf16_f32 v144, v52, v53
	v_cvt_pk_bf16_f32 v145, v54, v55
	v_cvt_pk_bf16_f32 v146, v48, v49
	v_cvt_pk_bf16_f32 v147, v50, v51
	global_store_dwordx4 v211, v[144:147], s[26:27] offset:64
	v_add_u32_e32 v211, 0x10000, v211
	s_waitcnt vmcnt(12)
	v_pk_add_f32 v[176:177], v[176:177], v[178:179]
	s_nop 0
	v_add_f32_e32 v214, v176, v177
	v_mov_b32_e32 v215, v214
	s_nop 1
	v_permlane16_swap_b32_e32 v214, v215
	s_nop 0
	v_add_f32_e32 v214, v214, v215
	v_mov_b32_e32 v215, v214
	s_nop 1
	v_permlane32_swap_b32_e32 v214, v215
	s_nop 0
	v_add_f32_e32 v214, v214, v215
	v_fmamk_f32 v214, v214, 0x3a800000, v248
	v_rsq_f32_e32 v216, v214
	s_nop 0
	v_pk_mul_f32 v[44:45], v[44:45], v[216:217] op_sel_hi:[1,0]
	v_pk_mul_f32 v[46:47], v[46:47], v[216:217] op_sel_hi:[1,0]
	v_pk_mul_f32 v[40:41], v[40:41], v[216:217] op_sel_hi:[1,0]
	v_pk_mul_f32 v[42:43], v[42:43], v[216:217] op_sel_hi:[1,0]
	v_pk_mul_f32 v[36:37], v[36:37], v[216:217] op_sel_hi:[1,0]
	v_pk_mul_f32 v[38:39], v[38:39], v[216:217] op_sel_hi:[1,0]
	v_pk_mul_f32 v[32:33], v[32:33], v[216:217] op_sel_hi:[1,0]
	v_pk_mul_f32 v[34:35], v[34:35], v[216:217] op_sel_hi:[1,0]
	v_pk_mul_f32 v[148:149], v[44:45], v[44:45]
	v_pk_fma_f32 v[148:149], v[46:47], v[46:47], v[148:149]
	v_pk_fma_f32 v[148:149], v[40:41], v[40:41], v[148:149]
	v_pk_fma_f32 v[148:149], v[42:43], v[42:43], v[148:149]
	v_pk_fma_f32 v[148:149], v[36:37], v[36:37], v[148:149]
	v_pk_fma_f32 v[148:149], v[38:39], v[38:39], v[148:149]
	v_pk_fma_f32 v[148:149], v[32:33], v[32:33], v[148:149]
	v_pk_fma_f32 v[148:149], v[34:35], v[34:35], v[148:149]
	v_add_f32_e32 v214, v148, v149
	v_mov_b32_e32 v215, v214
	s_nop 1
	v_permlane16_swap_b32_e32 v214, v215
	s_nop 0
	v_add_f32_e32 v214, v214, v215
	v_mov_b32_e32 v215, v214
	s_nop 1
	v_permlane32_swap_b32_e32 v214, v215
	s_nop 0
	v_add_f32_e32 v214, v214, v215
	v_fmamk_f32 v214, v214, 0x3c800000, v248
	v_rsq_f32_e32 v214, v214
	s_nop 0
	v_mul_f32_e32 v218, v155, v214
	v_pk_mul_f32 v[176:177], v[188:189], v[218:219] op_sel_hi:[1,0]
	v_pk_mul_f32 v[44:45], v[44:45], v[176:177]
	v_pk_mul_f32 v[176:177], v[190:191], v[218:219] op_sel_hi:[1,0]
	v_pk_mul_f32 v[46:47], v[46:47], v[176:177]
	v_pk_mul_f32 v[176:177], v[192:193], v[218:219] op_sel_hi:[1,0]
	v_pk_mul_f32 v[40:41], v[40:41], v[176:177]
	v_pk_mul_f32 v[176:177], v[194:195], v[218:219] op_sel_hi:[1,0]
	v_pk_mul_f32 v[42:43], v[42:43], v[176:177]
	v_cvt_pk_bf16_f32 v204, v44, v45
	v_cvt_pk_bf16_f32 v205, v46, v47
	v_cvt_pk_bf16_f32 v206, v40, v41
	v_cvt_pk_bf16_f32 v207, v42, v43
	global_store_dwordx4 v211, v[204:207], s[26:27]
	v_pk_mul_f32 v[176:177], v[196:197], v[218:219] op_sel_hi:[1,0]
	v_pk_mul_f32 v[36:37], v[36:37], v[176:177]
	v_pk_mul_f32 v[176:177], v[198:199], v[218:219] op_sel_hi:[1,0]
	v_pk_mul_f32 v[38:39], v[38:39], v[176:177]
	v_pk_mul_f32 v[176:177], v[200:201], v[218:219] op_sel_hi:[1,0]
	v_pk_mul_f32 v[32:33], v[32:33], v[176:177]
	v_pk_mul_f32 v[176:177], v[202:203], v[218:219] op_sel_hi:[1,0]
	v_pk_mul_f32 v[34:35], v[34:35], v[176:177]
	v_cvt_pk_bf16_f32 v144, v36, v37
	v_cvt_pk_bf16_f32 v145, v38, v39
	v_cvt_pk_bf16_f32 v146, v32, v33
	v_cvt_pk_bf16_f32 v147, v34, v35
	global_store_dwordx4 v211, v[144:147], s[26:27] offset:64
	v_add_u32_e32 v211, 0x10000, v211
	s_waitcnt vmcnt(13)
	v_pk_add_f32 v[180:181], v[180:181], v[182:183]
	s_nop 0
	v_add_f32_e32 v214, v180, v181
	v_mov_b32_e32 v215, v214
	s_nop 1
	v_permlane16_swap_b32_e32 v214, v215
	s_nop 0
	v_add_f32_e32 v214, v214, v215
	v_mov_b32_e32 v215, v214
	s_nop 1
	v_permlane32_swap_b32_e32 v214, v215
	s_nop 0
	v_add_f32_e32 v214, v214, v215
	v_fmamk_f32 v214, v214, 0x3a800000, v248
	v_rsq_f32_e32 v216, v214
	s_nop 0
	v_pk_mul_f32 v[28:29], v[28:29], v[216:217] op_sel_hi:[1,0]
	v_pk_mul_f32 v[30:31], v[30:31], v[216:217] op_sel_hi:[1,0]
	v_pk_mul_f32 v[24:25], v[24:25], v[216:217] op_sel_hi:[1,0]
	v_pk_mul_f32 v[26:27], v[26:27], v[216:217] op_sel_hi:[1,0]
	v_pk_mul_f32 v[20:21], v[20:21], v[216:217] op_sel_hi:[1,0]
	v_pk_mul_f32 v[22:23], v[22:23], v[216:217] op_sel_hi:[1,0]
	v_pk_mul_f32 v[16:17], v[16:17], v[216:217] op_sel_hi:[1,0]
	v_pk_mul_f32 v[18:19], v[18:19], v[216:217] op_sel_hi:[1,0]
	v_pk_mul_f32 v[148:149], v[28:29], v[28:29]
	v_pk_fma_f32 v[148:149], v[30:31], v[30:31], v[148:149]
	v_pk_fma_f32 v[148:149], v[24:25], v[24:25], v[148:149]
	v_pk_fma_f32 v[148:149], v[26:27], v[26:27], v[148:149]
	v_pk_fma_f32 v[148:149], v[20:21], v[20:21], v[148:149]
	v_pk_fma_f32 v[148:149], v[22:23], v[22:23], v[148:149]
	v_pk_fma_f32 v[148:149], v[16:17], v[16:17], v[148:149]
	v_pk_fma_f32 v[148:149], v[18:19], v[18:19], v[148:149]
	v_add_f32_e32 v214, v148, v149
	v_mov_b32_e32 v215, v214
	s_nop 1
	v_permlane16_swap_b32_e32 v214, v215
	s_nop 0
	v_add_f32_e32 v214, v214, v215
	v_mov_b32_e32 v215, v214
	s_nop 1
	v_permlane32_swap_b32_e32 v214, v215
	s_nop 0
	v_add_f32_e32 v214, v214, v215
	v_fmamk_f32 v214, v214, 0x3c800000, v248
	v_rsq_f32_e32 v214, v214
	s_nop 0
	v_mul_f32_e32 v218, v155, v214
	v_pk_mul_f32 v[180:181], v[188:189], v[218:219] op_sel_hi:[1,0]
	v_pk_mul_f32 v[28:29], v[28:29], v[180:181]
	v_pk_mul_f32 v[180:181], v[190:191], v[218:219] op_sel_hi:[1,0]
	v_pk_mul_f32 v[30:31], v[30:31], v[180:181]
	v_pk_mul_f32 v[180:181], v[192:193], v[218:219] op_sel_hi:[1,0]
	v_pk_mul_f32 v[24:25], v[24:25], v[180:181]
	v_pk_mul_f32 v[180:181], v[194:195], v[218:219] op_sel_hi:[1,0]
	v_pk_mul_f32 v[26:27], v[26:27], v[180:181]
	v_cvt_pk_bf16_f32 v204, v28, v29
	v_cvt_pk_bf16_f32 v205, v30, v31
	v_cvt_pk_bf16_f32 v206, v24, v25
	v_cvt_pk_bf16_f32 v207, v26, v27
	global_store_dwordx4 v211, v[204:207], s[26:27]
	v_pk_mul_f32 v[180:181], v[196:197], v[218:219] op_sel_hi:[1,0]
	v_pk_mul_f32 v[20:21], v[20:21], v[180:181]
	v_pk_mul_f32 v[180:181], v[198:199], v[218:219] op_sel_hi:[1,0]
	v_pk_mul_f32 v[22:23], v[22:23], v[180:181]
	v_pk_mul_f32 v[180:181], v[200:201], v[218:219] op_sel_hi:[1,0]
	v_pk_mul_f32 v[16:17], v[16:17], v[180:181]
	v_pk_mul_f32 v[180:181], v[202:203], v[218:219] op_sel_hi:[1,0]
	v_pk_mul_f32 v[18:19], v[18:19], v[180:181]
	v_cvt_pk_bf16_f32 v144, v20, v21
	v_cvt_pk_bf16_f32 v145, v22, v23
	v_cvt_pk_bf16_f32 v146, v16, v17
	v_cvt_pk_bf16_f32 v147, v18, v19
	global_store_dwordx4 v211, v[144:147], s[26:27] offset:64
	v_add_u32_e32 v211, 0x10000, v211
	s_waitcnt vmcnt(14)
	v_pk_add_f32 v[184:185], v[184:185], v[186:187]
	s_nop 0
	v_add_f32_e32 v214, v184, v185
	v_mov_b32_e32 v215, v214
	s_nop 1
	v_permlane16_swap_b32_e32 v214, v215
	s_nop 0
	v_add_f32_e32 v214, v214, v215
	v_mov_b32_e32 v215, v214
	s_nop 1
	v_permlane32_swap_b32_e32 v214, v215
	s_nop 0
	v_add_f32_e32 v214, v214, v215
	v_fmamk_f32 v214, v214, 0x3a800000, v248
	v_rsq_f32_e32 v216, v214
	s_nop 0
	v_pk_mul_f32 v[12:13], v[12:13], v[216:217] op_sel_hi:[1,0]
	v_pk_mul_f32 v[14:15], v[14:15], v[216:217] op_sel_hi:[1,0]
	v_pk_mul_f32 v[8:9], v[8:9], v[216:217] op_sel_hi:[1,0]
	v_pk_mul_f32 v[10:11], v[10:11], v[216:217] op_sel_hi:[1,0]
	v_pk_mul_f32 v[4:5], v[4:5], v[216:217] op_sel_hi:[1,0]
	v_pk_mul_f32 v[6:7], v[6:7], v[216:217] op_sel_hi:[1,0]
	v_pk_mul_f32 v[0:1], v[0:1], v[216:217] op_sel_hi:[1,0]
	v_pk_mul_f32 v[2:3], v[2:3], v[216:217] op_sel_hi:[1,0]
	v_pk_mul_f32 v[148:149], v[12:13], v[12:13]
	v_pk_fma_f32 v[148:149], v[14:15], v[14:15], v[148:149]
	v_pk_fma_f32 v[148:149], v[8:9], v[8:9], v[148:149]
	v_pk_fma_f32 v[148:149], v[10:11], v[10:11], v[148:149]
	v_pk_fma_f32 v[148:149], v[4:5], v[4:5], v[148:149]
	v_pk_fma_f32 v[148:149], v[6:7], v[6:7], v[148:149]
	v_pk_fma_f32 v[148:149], v[0:1], v[0:1], v[148:149]
	v_pk_fma_f32 v[148:149], v[2:3], v[2:3], v[148:149]
	v_add_f32_e32 v214, v148, v149
	v_mov_b32_e32 v215, v214
	s_nop 1
	v_permlane16_swap_b32_e32 v214, v215
	s_nop 0
	v_add_f32_e32 v214, v214, v215
	v_mov_b32_e32 v215, v214
	s_nop 1
	v_permlane32_swap_b32_e32 v214, v215
	s_nop 0
	v_add_f32_e32 v214, v214, v215
	v_fmamk_f32 v214, v214, 0x3c800000, v248
	v_rsq_f32_e32 v214, v214
	s_nop 0
	v_mul_f32_e32 v218, v155, v214
	v_pk_mul_f32 v[184:185], v[188:189], v[218:219] op_sel_hi:[1,0]
	v_pk_mul_f32 v[12:13], v[12:13], v[184:185]
	v_pk_mul_f32 v[184:185], v[190:191], v[218:219] op_sel_hi:[1,0]
	v_pk_mul_f32 v[14:15], v[14:15], v[184:185]
	v_pk_mul_f32 v[184:185], v[192:193], v[218:219] op_sel_hi:[1,0]
	v_pk_mul_f32 v[8:9], v[8:9], v[184:185]
	v_pk_mul_f32 v[184:185], v[194:195], v[218:219] op_sel_hi:[1,0]
	v_pk_mul_f32 v[10:11], v[10:11], v[184:185]
	v_cvt_pk_bf16_f32 v204, v12, v13
	v_cvt_pk_bf16_f32 v205, v14, v15
	v_cvt_pk_bf16_f32 v206, v8, v9
	v_cvt_pk_bf16_f32 v207, v10, v11
	global_store_dwordx4 v211, v[204:207], s[26:27]
	v_pk_mul_f32 v[184:185], v[196:197], v[218:219] op_sel_hi:[1,0]
	v_pk_mul_f32 v[4:5], v[4:5], v[184:185]
	v_pk_mul_f32 v[184:185], v[198:199], v[218:219] op_sel_hi:[1,0]
	v_pk_mul_f32 v[6:7], v[6:7], v[184:185]
	v_pk_mul_f32 v[184:185], v[200:201], v[218:219] op_sel_hi:[1,0]
	v_pk_mul_f32 v[0:1], v[0:1], v[184:185]
	v_pk_mul_f32 v[184:185], v[202:203], v[218:219] op_sel_hi:[1,0]
	v_pk_mul_f32 v[2:3], v[2:3], v[184:185]
	v_cvt_pk_bf16_f32 v144, v4, v5
	v_cvt_pk_bf16_f32 v145, v6, v7
	v_cvt_pk_bf16_f32 v146, v0, v1
	v_cvt_pk_bf16_f32 v147, v2, v3
	global_store_dwordx4 v211, v[144:147], s[26:27] offset:64
	s_and_b64 vcc, exec, s[4:5]
	s_mov_b64 s[26:27], s[22:23]
	s_cbranch_vccz .LBB0_691
	s_waitcnt vmcnt(0)
	s_cmpk_gt_u32 s54, 0xff
	s_cbranch_scc1 .LBB0_702
	s_barrier

.LBB0_823:
	s_add_u32 s26, s24, 0xfffc0080
	s_addc_u32 s27, s25, -1
	s_add_i32 s65, 0, 0x10000
	v_add_u32_e32 v154, s65, v143
	ds_read_b128 v[138:141], v154
	ds_read_b128 v[146:149], v154 offset:1024
	ds_read_b128 v[150:153], v154 offset:2048
	ds_read_b128 v[154:157], v154 offset:3072
	s_cmp_eq_u32 s51, 12
	s_cselect_b32 s29, s19, s27
	s_cselect_b32 s28, s38, s26
	s_cselect_b32 s27, s17, s50
	s_cselect_b32 s26, s39, s46
	v_lshl_add_u64 v[190:191], s[24:25], 0, v[134:135]
	s_add_i32 m0, s58, 0xc000
	ds_read_b128 v[158:161], v145
	ds_read_b128 v[162:165], v145 offset:1024
	ds_read_b128 v[166:169], v145 offset:2048
	ds_read_b128 v[170:173], v145 offset:3072
	ds_read_b128 v[174:177], v145 offset:4096
	ds_read_b128 v[178:181], v145 offset:5120
	ds_read_b128 v[182:185], v145 offset:6144
	ds_read_b128 v[186:189], v145 offset:7168
	global_load_lds_dwordx4 v[190:191], off
	v_lshl_add_u64 v[190:191], s[24:25], 0, v[136:137]
	s_add_i32 m0, s58, 0xe000
	s_nop 0
	global_load_lds_dwordx4 v[190:191], off
	s_waitcnt lgkmcnt(8)
	s_barrier
	s_waitcnt lgkmcnt(0)
	s_setprio 1
	s_waitcnt lgkmcnt(0)
	v_mfma_f32_16x16x32_bf16 v[124:127], v[138:141], v[158:161], v[124:127]
	v_mfma_f32_16x16x32_bf16 v[120:123], v[150:153], v[158:161], v[120:123]
	v_mfma_f32_16x16x32_bf16 v[108:111], v[138:141], v[166:169], v[108:111]
	v_mfma_f32_16x16x32_bf16 v[104:107], v[150:153], v[166:169], v[104:107]
	v_mfma_f32_16x16x32_bf16 v[92:95], v[138:141], v[174:177], v[92:95]
	v_mfma_f32_16x16x32_bf16 v[88:91], v[150:153], v[174:177], v[88:91]
	v_mfma_f32_16x16x32_bf16 v[76:79], v[138:141], v[182:185], v[76:79]
	v_mfma_f32_16x16x32_bf16 v[72:75], v[150:153], v[182:185], v[72:75]
	v_mfma_f32_16x16x32_bf16 v[124:127], v[146:149], v[162:165], v[124:127]
	v_mfma_f32_16x16x32_bf16 v[120:123], v[154:157], v[162:165], v[120:123]
	v_mfma_f32_16x16x32_bf16 v[108:111], v[146:149], v[170:173], v[108:111]
	v_mfma_f32_16x16x32_bf16 v[104:107], v[154:157], v[170:173], v[104:107]
	v_mfma_f32_16x16x32_bf16 v[92:95], v[146:149], v[178:181], v[92:95]
	v_mfma_f32_16x16x32_bf16 v[88:91], v[154:157], v[178:181], v[88:91]
	v_mfma_f32_16x16x32_bf16 v[76:79], v[146:149], v[186:189], v[76:79]
	v_mfma_f32_16x16x32_bf16 v[72:75], v[154:157], v[186:189], v[72:75]
	s_setprio 0
	s_barrier
	s_add_i32 s68, 0, 0x14000
	s_add_i32 s65, s65, s57
	v_add_u32_e32 v202, s68, v143
	v_lshl_add_u64 v[206:207], s[26:27], 0, v[208:209]
	s_mov_b32 m0, s65
	ds_read_b128 v[190:193], v202
	ds_read_b128 v[194:197], v202 offset:1024
	ds_read_b128 v[198:201], v202 offset:2048
	ds_read_b128 v[202:205], v202 offset:3072
	global_load_lds_dwordx4 v[206:207], off
	v_lshl_add_u64 v[210:211], s[26:27], 0, v[128:129]
	s_add_i32 m0, s65, 0x2000
	s_nop 0
	global_load_lds_dwordx4 v[210:211], off
	s_barrier
	s_waitcnt lgkmcnt(0)
	s_setprio 1
	s_waitcnt lgkmcnt(0)
	v_mfma_f32_16x16x32_bf16 v[116:119], v[190:193], v[158:161], v[116:119]
	v_mfma_f32_16x16x32_bf16 v[112:115], v[198:201], v[158:161], v[112:115]
	v_mfma_f32_16x16x32_bf16 v[100:103], v[190:193], v[166:169], v[100:103]
	v_mfma_f32_16x16x32_bf16 v[96:99], v[198:201], v[166:169], v[96:99]
	v_mfma_f32_16x16x32_bf16 v[84:87], v[190:193], v[174:177], v[84:87]
	v_mfma_f32_16x16x32_bf16 v[80:83], v[198:201], v[174:177], v[80:83]
	v_mfma_f32_16x16x32_bf16 v[68:71], v[190:193], v[182:185], v[68:71]
	v_mfma_f32_16x16x32_bf16 v[64:67], v[198:201], v[182:185], v[64:67]
	v_mfma_f32_16x16x32_bf16 v[116:119], v[194:197], v[162:165], v[116:119]
	v_mfma_f32_16x16x32_bf16 v[112:115], v[202:205], v[162:165], v[112:115]
	v_mfma_f32_16x16x32_bf16 v[100:103], v[194:197], v[170:173], v[100:103]
	v_mfma_f32_16x16x32_bf16 v[96:99], v[202:205], v[170:173], v[96:99]
	v_mfma_f32_16x16x32_bf16 v[84:87], v[194:197], v[178:181], v[84:87]
	v_mfma_f32_16x16x32_bf16 v[80:83], v[202:205], v[178:181], v[80:83]
	v_mfma_f32_16x16x32_bf16 v[68:71], v[194:197], v[186:189], v[68:71]
	v_mfma_f32_16x16x32_bf16 v[64:67], v[202:205], v[186:189], v[64:67]
	s_setprio 0
	s_mov_b32 m0, s58
	v_lshl_add_u64 v[214:215], s[28:29], 0, v[132:133]
	s_barrier
	ds_read_b128 v[158:161], v145 offset:16384
	ds_read_b128 v[162:165], v145 offset:17408
	ds_read_b128 v[166:169], v145 offset:18432
	ds_read_b128 v[170:173], v145 offset:19456
	ds_read_b128 v[174:177], v145 offset:20480
	ds_read_b128 v[178:181], v145 offset:21504
	ds_read_b128 v[182:185], v145 offset:22528
	ds_read_b128 v[186:189], v145 offset:23552
	global_load_lds_dwordx4 v[214:215], off
	v_lshl_add_u64 v[216:217], s[28:29], 0, v[130:131]
	s_mov_b32 m0, s59
	s_nop 0
	global_load_lds_dwordx4 v[216:217], off
	s_barrier
	s_waitcnt lgkmcnt(0)
	s_setprio 1
	s_waitcnt lgkmcnt(0)
	v_mfma_f32_16x16x32_bf16 v[60:63], v[138:141], v[158:161], v[60:63]
	v_mfma_f32_16x16x32_bf16 v[56:59], v[150:153], v[158:161], v[56:59]
	v_mfma_f32_16x16x32_bf16 v[44:47], v[138:141], v[166:169], v[44:47]
	v_mfma_f32_16x16x32_bf16 v[40:43], v[150:153], v[166:169], v[40:43]
	v_mfma_f32_16x16x32_bf16 v[28:31], v[138:141], v[174:177], v[28:31]
	v_mfma_f32_16x16x32_bf16 v[24:27], v[150:153], v[174:177], v[24:27]
	v_mfma_f32_16x16x32_bf16 v[12:15], v[138:141], v[182:185], v[12:15]
	v_mfma_f32_16x16x32_bf16 v[8:11], v[150:153], v[182:185], v[8:11]
	v_mfma_f32_16x16x32_bf16 v[60:63], v[146:149], v[162:165], v[60:63]
	v_mfma_f32_16x16x32_bf16 v[56:59], v[154:157], v[162:165], v[56:59]
	v_mfma_f32_16x16x32_bf16 v[44:47], v[146:149], v[170:173], v[44:47]
	v_mfma_f32_16x16x32_bf16 v[40:43], v[154:157], v[170:173], v[40:43]
	v_mfma_f32_16x16x32_bf16 v[28:31], v[146:149], v[178:181], v[28:31]
	v_mfma_f32_16x16x32_bf16 v[24:27], v[154:157], v[178:181], v[24:27]
	v_mfma_f32_16x16x32_bf16 v[12:15], v[146:149], v[186:189], v[12:15]
	v_mfma_f32_16x16x32_bf16 v[8:11], v[154:157], v[186:189], v[8:11]
	s_setprio 0
	s_barrier
	s_add_u32 s66, s26, 0x40000
	s_addc_u32 s67, s27, 0
	s_add_i32 s65, s68, s57
	v_lshl_add_u64 v[138:139], s[66:67], 0, v[208:209]
	s_mov_b32 m0, s65
	s_nop 0
	global_load_lds_dwordx4 v[138:139], off
	v_lshl_add_u64 v[138:139], s[66:67], 0, v[128:129]
	s_add_i32 m0, s65, 0x2000
	s_nop 0
	global_load_lds_dwordx4 v[138:139], off
	s_waitcnt vmcnt(6)
	s_barrier
	s_setprio 1
	v_mfma_f32_16x16x32_bf16 v[52:55], v[190:193], v[158:161], v[52:55]
	v_mfma_f32_16x16x32_bf16 v[48:51], v[198:201], v[158:161], v[48:51]
	v_mfma_f32_16x16x32_bf16 v[36:39], v[190:193], v[166:169], v[36:39]
	v_mfma_f32_16x16x32_bf16 v[32:35], v[198:201], v[166:169], v[32:35]
	v_mfma_f32_16x16x32_bf16 v[20:23], v[190:193], v[174:177], v[20:23]
	v_mfma_f32_16x16x32_bf16 v[16:19], v[198:201], v[174:177], v[16:19]
	v_mfma_f32_16x16x32_bf16 v[4:7], v[190:193], v[182:185], v[4:7]
	v_mfma_f32_16x16x32_bf16 v[0:3], v[198:201], v[182:185], v[0:3]
	v_mfma_f32_16x16x32_bf16 v[52:55], v[194:197], v[162:165], v[52:55]
	v_mfma_f32_16x16x32_bf16 v[48:51], v[202:205], v[162:165], v[48:51]
	v_mfma_f32_16x16x32_bf16 v[36:39], v[194:197], v[170:173], v[36:39]
	v_mfma_f32_16x16x32_bf16 v[32:35], v[202:205], v[170:173], v[32:35]
	v_mfma_f32_16x16x32_bf16 v[20:23], v[194:197], v[178:181], v[20:23]
	v_mfma_f32_16x16x32_bf16 v[16:19], v[202:205], v[178:181], v[16:19]
	v_mfma_f32_16x16x32_bf16 v[4:7], v[194:197], v[186:189], v[4:7]
	v_mfma_f32_16x16x32_bf16 v[0:3], v[202:205], v[186:189], v[0:3]
	s_setprio 0
	s_add_i32 s65, 0, 0x18000
	v_add_u32_e32 v154, s65, v143
	s_barrier
	ds_read_b128 v[138:141], v154
	ds_read_b128 v[146:149], v154 offset:1024
	ds_read_b128 v[150:153], v154 offset:2048
	ds_read_b128 v[154:157], v154 offset:3072
	s_add_u32 s28, s28, 0x40000
	s_addc_u32 s29, s29, 0
	s_mov_b32 m0, s60
	v_lshl_add_u64 v[190:191], s[28:29], 0, v[132:133]
	ds_read_b128 v[158:161], v145 offset:32768
	ds_read_b128 v[162:165], v145 offset:33792
	ds_read_b128 v[166:169], v145 offset:34816
	ds_read_b128 v[170:173], v145 offset:35840
	ds_read_b128 v[174:177], v145 offset:36864
	ds_read_b128 v[178:181], v145 offset:37888
	ds_read_b128 v[182:185], v145 offset:38912
	ds_read_b128 v[186:189], v145 offset:39936
	global_load_lds_dwordx4 v[190:191], off
	v_lshl_add_u64 v[190:191], s[28:29], 0, v[130:131]
	s_mov_b32 m0, s61
	s_nop 0
	global_load_lds_dwordx4 v[190:191], off
	s_waitcnt lgkmcnt(8)
	s_barrier
	s_waitcnt lgkmcnt(0)
	s_setprio 1
	s_waitcnt lgkmcnt(0)
	v_mfma_f32_16x16x32_bf16 v[124:127], v[138:141], v[158:161], v[124:127]
	v_mfma_f32_16x16x32_bf16 v[120:123], v[150:153], v[158:161], v[120:123]
	v_mfma_f32_16x16x32_bf16 v[108:111], v[138:141], v[166:169], v[108:111]
	v_mfma_f32_16x16x32_bf16 v[104:107], v[150:153], v[166:169], v[104:107]
	v_mfma_f32_16x16x32_bf16 v[92:95], v[138:141], v[174:177], v[92:95]
	v_mfma_f32_16x16x32_bf16 v[88:91], v[150:153], v[174:177], v[88:91]
	v_mfma_f32_16x16x32_bf16 v[76:79], v[138:141], v[182:185], v[76:79]
	v_mfma_f32_16x16x32_bf16 v[72:75], v[150:153], v[182:185], v[72:75]
	v_mfma_f32_16x16x32_bf16 v[124:127], v[146:149], v[162:165], v[124:127]
	v_mfma_f32_16x16x32_bf16 v[120:123], v[154:157], v[162:165], v[120:123]
	v_mfma_f32_16x16x32_bf16 v[108:111], v[146:149], v[170:173], v[108:111]
	v_mfma_f32_16x16x32_bf16 v[104:107], v[154:157], v[170:173], v[104:107]
	v_mfma_f32_16x16x32_bf16 v[92:95], v[146:149], v[178:181], v[92:95]
	v_mfma_f32_16x16x32_bf16 v[88:91], v[154:157], v[178:181], v[88:91]
	v_mfma_f32_16x16x32_bf16 v[76:79], v[146:149], v[186:189], v[76:79]
	v_mfma_f32_16x16x32_bf16 v[72:75], v[154:157], v[186:189], v[72:75]
	s_setprio 0
	s_barrier
	s_add_i32 s28, 0, 0x1c000
	s_add_i32 s29, s65, s57
	v_add_u32_e32 v202, s28, v143
	v_lshl_add_u64 v[206:207], v[206:207], 0, s[40:41]
	s_mov_b32 m0, s29
	ds_read_b128 v[190:193], v202
	ds_read_b128 v[194:197], v202 offset:1024
	ds_read_b128 v[198:201], v202 offset:2048
	ds_read_b128 v[202:205], v202 offset:3072
	global_load_lds_dwordx4 v[206:207], off
	v_lshl_add_u64 v[206:207], v[210:211], 0, s[40:41]
	s_add_i32 m0, s29, 0x2000
	s_nop 0
	global_load_lds_dwordx4 v[206:207], off
	s_barrier
	s_waitcnt lgkmcnt(0)
	s_setprio 1
	s_waitcnt lgkmcnt(0)
	v_mfma_f32_16x16x32_bf16 v[116:119], v[190:193], v[158:161], v[116:119]
	v_mfma_f32_16x16x32_bf16 v[112:115], v[198:201], v[158:161], v[112:115]
	v_mfma_f32_16x16x32_bf16 v[100:103], v[190:193], v[166:169], v[100:103]
	v_mfma_f32_16x16x32_bf16 v[96:99], v[198:201], v[166:169], v[96:99]
	v_mfma_f32_16x16x32_bf16 v[84:87], v[190:193], v[174:177], v[84:87]
	v_mfma_f32_16x16x32_bf16 v[80:83], v[198:201], v[174:177], v[80:83]
	v_mfma_f32_16x16x32_bf16 v[68:71], v[190:193], v[182:185], v[68:71]
	v_mfma_f32_16x16x32_bf16 v[64:67], v[198:201], v[182:185], v[64:67]
	v_mfma_f32_16x16x32_bf16 v[116:119], v[194:197], v[162:165], v[116:119]
	v_mfma_f32_16x16x32_bf16 v[112:115], v[202:205], v[162:165], v[112:115]
	v_mfma_f32_16x16x32_bf16 v[100:103], v[194:197], v[170:173], v[100:103]
	v_mfma_f32_16x16x32_bf16 v[96:99], v[202:205], v[170:173], v[96:99]
	v_mfma_f32_16x16x32_bf16 v[84:87], v[194:197], v[178:181], v[84:87]
	v_mfma_f32_16x16x32_bf16 v[80:83], v[202:205], v[178:181], v[80:83]
	v_mfma_f32_16x16x32_bf16 v[68:71], v[194:197], v[186:189], v[68:71]
	v_mfma_f32_16x16x32_bf16 v[64:67], v[202:205], v[186:189], v[64:67]
	s_setprio 0
	s_mov_b32 m0, s62
	v_lshl_add_u64 v[206:207], v[214:215], 0, s[40:41]
	s_barrier
	ds_read_b128 v[158:161], v145 offset:49152
	ds_read_b128 v[162:165], v145 offset:50176
	ds_read_b128 v[166:169], v145 offset:51200
	ds_read_b128 v[170:173], v145 offset:52224
	ds_read_b128 v[174:177], v145 offset:53248
	ds_read_b128 v[178:181], v145 offset:54272
	ds_read_b128 v[182:185], v145 offset:55296
	ds_read_b128 v[186:189], v145 offset:56320
	global_load_lds_dwordx4 v[206:207], off
	v_lshl_add_u64 v[206:207], v[216:217], 0, s[40:41]
	s_mov_b32 m0, s63
	s_nop 0
	global_load_lds_dwordx4 v[206:207], off
	s_barrier
	s_waitcnt lgkmcnt(0)
	s_setprio 1
	s_waitcnt lgkmcnt(0)
	v_mfma_f32_16x16x32_bf16 v[60:63], v[138:141], v[158:161], v[60:63]
	v_mfma_f32_16x16x32_bf16 v[56:59], v[150:153], v[158:161], v[56:59]
	v_mfma_f32_16x16x32_bf16 v[44:47], v[138:141], v[166:169], v[44:47]
	v_mfma_f32_16x16x32_bf16 v[40:43], v[150:153], v[166:169], v[40:43]
	v_mfma_f32_16x16x32_bf16 v[28:31], v[138:141], v[174:177], v[28:31]
	v_mfma_f32_16x16x32_bf16 v[24:27], v[150:153], v[174:177], v[24:27]
	v_mfma_f32_16x16x32_bf16 v[12:15], v[138:141], v[182:185], v[12:15]
	v_mfma_f32_16x16x32_bf16 v[8:11], v[150:153], v[182:185], v[8:11]
	v_mfma_f32_16x16x32_bf16 v[60:63], v[146:149], v[162:165], v[60:63]
	v_mfma_f32_16x16x32_bf16 v[56:59], v[154:157], v[162:165], v[56:59]
	v_mfma_f32_16x16x32_bf16 v[44:47], v[146:149], v[170:173], v[44:47]
	v_mfma_f32_16x16x32_bf16 v[40:43], v[154:157], v[170:173], v[40:43]
	v_mfma_f32_16x16x32_bf16 v[28:31], v[146:149], v[178:181], v[28:31]
	v_mfma_f32_16x16x32_bf16 v[24:27], v[154:157], v[178:181], v[24:27]
	v_mfma_f32_16x16x32_bf16 v[12:15], v[146:149], v[186:189], v[12:15]
	v_mfma_f32_16x16x32_bf16 v[8:11], v[154:157], v[186:189], v[8:11]
	s_setprio 0
	s_barrier
	s_add_u32 s26, s26, 0x40080
	s_addc_u32 s27, s27, 0
	s_add_i32 s28, s28, s57
	v_lshl_add_u64 v[138:139], s[26:27], 0, v[208:209]
	s_mov_b32 m0, s28
	s_nop 0
	global_load_lds_dwordx4 v[138:139], off
	v_lshl_add_u64 v[138:139], s[26:27], 0, v[128:129]
	s_add_i32 m0, s28, 0x2000
	s_nop 0
	global_load_lds_dwordx4 v[138:139], off
	s_waitcnt vmcnt(6)
	s_barrier
	s_setprio 1
	v_mfma_f32_16x16x32_bf16 v[52:55], v[190:193], v[158:161], v[52:55]
	v_mfma_f32_16x16x32_bf16 v[48:51], v[198:201], v[158:161], v[48:51]
	v_mfma_f32_16x16x32_bf16 v[36:39], v[190:193], v[166:169], v[36:39]
	v_mfma_f32_16x16x32_bf16 v[32:35], v[198:201], v[166:169], v[32:35]
	v_mfma_f32_16x16x32_bf16 v[20:23], v[190:193], v[174:177], v[20:23]
	v_mfma_f32_16x16x32_bf16 v[16:19], v[198:201], v[174:177], v[16:19]
	v_mfma_f32_16x16x32_bf16 v[4:7], v[190:193], v[182:185], v[4:7]
	v_mfma_f32_16x16x32_bf16 v[0:3], v[198:201], v[182:185], v[0:3]
	v_mfma_f32_16x16x32_bf16 v[52:55], v[194:197], v[162:165], v[52:55]
	v_mfma_f32_16x16x32_bf16 v[48:51], v[202:205], v[162:165], v[48:51]
	v_mfma_f32_16x16x32_bf16 v[36:39], v[194:197], v[170:173], v[36:39]
	v_mfma_f32_16x16x32_bf16 v[32:35], v[202:205], v[170:173], v[32:35]
	v_mfma_f32_16x16x32_bf16 v[20:23], v[194:197], v[178:181], v[20:23]
	v_mfma_f32_16x16x32_bf16 v[16:19], v[202:205], v[178:181], v[16:19]
	v_mfma_f32_16x16x32_bf16 v[4:7], v[194:197], v[186:189], v[4:7]
	v_mfma_f32_16x16x32_bf16 v[0:3], v[202:205], v[186:189], v[0:3]
	s_setprio 0
	s_add_i32 s51, s51, 2
	s_add_u32 s24, s24, 0x100
	s_addc_u32 s25, s25, 0
	s_add_u32 s46, s46, 0x100
	s_addc_u32 s50, s50, 0
	s_cmp_gt_u32 s51, 13
	s_barrier
	s_cbranch_scc0 .LBB0_823
	v_lshl_add_u32 v140, s35, 8, v142
	v_lshl_or_b32 v141, s34, 8, v144
	s_mov_b32 s34, s16
	s_mov_b32 s35, s18
	s_mov_b64 s[26:27], s[22:23]
	s_mov_b64 s[24:25], s[20:21]
	v_mbcnt_lo_u32_b32 v206, -1, 0
	v_mbcnt_hi_u32_b32 v206, -1, v206
	v_and_b32_e32 v206, 48, v206
	v_lshl_add_u32 v206, v140, 6, v206
	v_lshlrev_b32_e32 v207, 11, v140
	v_lshl_add_u32 v207, v141, 1, v207
	global_load_dwordx4 v[146:149], v206, s[14:15]
	global_load_dwordx4 v[150:153], v206, s[14:15] offset:1024
	global_load_dwordx4 v[154:157], v206, s[14:15] offset:2048
	global_load_dwordx4 v[158:161], v206, s[14:15] offset:3072
	v_add_u32_e32 v206, 0x2000, v206
	global_load_dwordx4 v[162:165], v206, s[14:15]
	global_load_dwordx4 v[166:169], v206, s[14:15] offset:1024
	global_load_dwordx4 v[170:173], v206, s[14:15] offset:2048
	global_load_dwordx4 v[174:177], v206, s[14:15] offset:3072
	s_waitcnt vmcnt(7)
	v_pk_add_f32 v[146:147], v[146:147], v[148:149]
	s_nop 0
	v_add_f32_e32 v214, v146, v147
	v_mov_b32_e32 v215, v214
	s_nop 1
	v_permlane16_swap_b32_e32 v214, v215
	s_nop 0
	v_add_f32_e32 v214, v214, v215
	v_mov_b32_e32 v215, v214
	s_nop 1
	v_permlane32_swap_b32_e32 v214, v215
	s_nop 0
	v_add_f32_e32 v214, v214, v215
	v_fmamk_f32 v214, v214, 0x3a800000, v248
	v_rsq_f32_e32 v178, v214
	s_nop 0
	v_pk_mul_f32 v[124:125], v[124:125], v[178:179] op_sel_hi:[1,0]
	v_pk_mul_f32 v[126:127], v[126:127], v[178:179] op_sel_hi:[1,0]
	v_pk_mul_f32 v[120:121], v[120:121], v[178:179] op_sel_hi:[1,0]
	v_pk_mul_f32 v[122:123], v[122:123], v[178:179] op_sel_hi:[1,0]
	v_cvt_pk_bf16_f32 v198, v124, v125
	v_cvt_pk_bf16_f32 v199, v126, v127
	v_cvt_pk_bf16_f32 v200, v120, v121
	v_cvt_pk_bf16_f32 v201, v122, v123
	global_store_dwordx4 v207, v[198:201], s[10:11]
	v_pk_mul_f32 v[116:117], v[116:117], v[178:179] op_sel_hi:[1,0]
	v_pk_mul_f32 v[118:119], v[118:119], v[178:179] op_sel_hi:[1,0]
	v_pk_mul_f32 v[112:113], v[112:113], v[178:179] op_sel_hi:[1,0]
	v_pk_mul_f32 v[114:115], v[114:115], v[178:179] op_sel_hi:[1,0]
	v_cvt_pk_bf16_f32 v202, v116, v117
	v_cvt_pk_bf16_f32 v203, v118, v119
	v_cvt_pk_bf16_f32 v204, v112, v113
	v_cvt_pk_bf16_f32 v205, v114, v115
	global_store_dwordx4 v207, v[202:205], s[10:11] offset:256
	v_add_u32_e32 v207, 0x8000, v207
	s_waitcnt vmcnt(8)
	v_pk_add_f32 v[150:151], v[150:151], v[152:153]
	s_nop 0
	v_add_f32_e32 v214, v150, v151
	v_mov_b32_e32 v215, v214
	s_nop 1
	v_permlane16_swap_b32_e32 v214, v215
	s_nop 0
	v_add_f32_e32 v214, v214, v215
	v_mov_b32_e32 v215, v214
	s_nop 1
	v_permlane32_swap_b32_e32 v214, v215
	s_nop 0
	v_add_f32_e32 v214, v214, v215
	v_fmamk_f32 v214, v214, 0x3a800000, v248
	v_rsq_f32_e32 v180, v214
	s_nop 0
	v_pk_mul_f32 v[108:109], v[108:109], v[180:181] op_sel_hi:[1,0]
	v_pk_mul_f32 v[110:111], v[110:111], v[180:181] op_sel_hi:[1,0]
	v_pk_mul_f32 v[104:105], v[104:105], v[180:181] op_sel_hi:[1,0]
	v_pk_mul_f32 v[106:107], v[106:107], v[180:181] op_sel_hi:[1,0]
	v_cvt_pk_bf16_f32 v198, v108, v109
	v_cvt_pk_bf16_f32 v199, v110, v111
	v_cvt_pk_bf16_f32 v200, v104, v105
	v_cvt_pk_bf16_f32 v201, v106, v107
	global_store_dwordx4 v207, v[198:201], s[10:11]
	v_pk_mul_f32 v[100:101], v[100:101], v[180:181] op_sel_hi:[1,0]
	v_pk_mul_f32 v[102:103], v[102:103], v[180:181] op_sel_hi:[1,0]
	v_pk_mul_f32 v[96:97], v[96:97], v[180:181] op_sel_hi:[1,0]
	v_pk_mul_f32 v[98:99], v[98:99], v[180:181] op_sel_hi:[1,0]
	v_cvt_pk_bf16_f32 v202, v100, v101
	v_cvt_pk_bf16_f32 v203, v102, v103
	v_cvt_pk_bf16_f32 v204, v96, v97
	v_cvt_pk_bf16_f32 v205, v98, v99
	global_store_dwordx4 v207, v[202:205], s[10:11] offset:256
	v_add_u32_e32 v207, 0x8000, v207
	s_waitcnt vmcnt(9)
	v_pk_add_f32 v[154:155], v[154:155], v[156:157]
	s_nop 0
	v_add_f32_e32 v214, v154, v155
	v_mov_b32_e32 v215, v214
	s_nop 1
	v_permlane16_swap_b32_e32 v214, v215
	s_nop 0
	v_add_f32_e32 v214, v214, v215
	v_mov_b32_e32 v215, v214
	s_nop 1
	v_permlane32_swap_b32_e32 v214, v215
	s_nop 0
	v_add_f32_e32 v214, v214, v215
	v_fmamk_f32 v214, v214, 0x3a800000, v248
	v_rsq_f32_e32 v182, v214
	s_nop 0
	v_pk_mul_f32 v[92:93], v[92:93], v[182:183] op_sel_hi:[1,0]
	v_pk_mul_f32 v[94:95], v[94:95], v[182:183] op_sel_hi:[1,0]
	v_pk_mul_f32 v[88:89], v[88:89], v[182:183] op_sel_hi:[1,0]
	v_pk_mul_f32 v[90:91], v[90:91], v[182:183] op_sel_hi:[1,0]
	v_cvt_pk_bf16_f32 v198, v92, v93
	v_cvt_pk_bf16_f32 v199, v94, v95
	v_cvt_pk_bf16_f32 v200, v88, v89
	v_cvt_pk_bf16_f32 v201, v90, v91
	global_store_dwordx4 v207, v[198:201], s[10:11]
	v_pk_mul_f32 v[84:85], v[84:85], v[182:183] op_sel_hi:[1,0]
	v_pk_mul_f32 v[86:87], v[86:87], v[182:183] op_sel_hi:[1,0]
	v_pk_mul_f32 v[80:81], v[80:81], v[182:183] op_sel_hi:[1,0]
	v_pk_mul_f32 v[82:83], v[82:83], v[182:183] op_sel_hi:[1,0]
	v_cvt_pk_bf16_f32 v202, v84, v85
	v_cvt_pk_bf16_f32 v203, v86, v87
	v_cvt_pk_bf16_f32 v204, v80, v81
	v_cvt_pk_bf16_f32 v205, v82, v83
	global_store_dwordx4 v207, v[202:205], s[10:11] offset:256
	v_add_u32_e32 v207, 0x8000, v207
	s_waitcnt vmcnt(10)
	v_pk_add_f32 v[158:159], v[158:159], v[160:161]
	s_nop 0
	v_add_f32_e32 v214, v158, v159
	v_mov_b32_e32 v215, v214
	s_nop 1
	v_permlane16_swap_b32_e32 v214, v215
	s_nop 0
	v_add_f32_e32 v214, v214, v215
	v_mov_b32_e32 v215, v214
	s_nop 1
	v_permlane32_swap_b32_e32 v214, v215
	s_nop 0
	v_add_f32_e32 v214, v214, v215
	v_fmamk_f32 v214, v214, 0x3a800000, v248
	v_rsq_f32_e32 v184, v214
	s_nop 0
	v_pk_mul_f32 v[76:77], v[76:77], v[184:185] op_sel_hi:[1,0]
	v_pk_mul_f32 v[78:79], v[78:79], v[184:185] op_sel_hi:[1,0]
	v_pk_mul_f32 v[72:73], v[72:73], v[184:185] op_sel_hi:[1,0]
	v_pk_mul_f32 v[74:75], v[74:75], v[184:185] op_sel_hi:[1,0]
	v_cvt_pk_bf16_f32 v198, v76, v77
	v_cvt_pk_bf16_f32 v199, v78, v79
	v_cvt_pk_bf16_f32 v200, v72, v73
	v_cvt_pk_bf16_f32 v201, v74, v75
	global_store_dwordx4 v207, v[198:201], s[10:11]
	v_pk_mul_f32 v[68:69], v[68:69], v[184:185] op_sel_hi:[1,0]
	v_pk_mul_f32 v[70:71], v[70:71], v[184:185] op_sel_hi:[1,0]
	v_pk_mul_f32 v[64:65], v[64:65], v[184:185] op_sel_hi:[1,0]
	v_pk_mul_f32 v[66:67], v[66:67], v[184:185] op_sel_hi:[1,0]
	v_cvt_pk_bf16_f32 v202, v68, v69
	v_cvt_pk_bf16_f32 v203, v70, v71
	v_cvt_pk_bf16_f32 v204, v64, v65
	v_cvt_pk_bf16_f32 v205, v66, v67
	global_store_dwordx4 v207, v[202:205], s[10:11] offset:256
	v_add_u32_e32 v207, 0x28000, v207
	s_waitcnt vmcnt(11)
	v_pk_add_f32 v[162:163], v[162:163], v[164:165]
	s_nop 0
	v_add_f32_e32 v214, v162, v163
	v_mov_b32_e32 v215, v214
	s_nop 1
	v_permlane16_swap_b32_e32 v214, v215
	s_nop 0
	v_add_f32_e32 v214, v214, v215
	v_mov_b32_e32 v215, v214
	s_nop 1
	v_permlane32_swap_b32_e32 v214, v215
	s_nop 0
	v_add_f32_e32 v214, v214, v215
	v_fmamk_f32 v214, v214, 0x3a800000, v248
	v_rsq_f32_e32 v186, v214
	s_nop 0
	v_pk_mul_f32 v[60:61], v[60:61], v[186:187] op_sel_hi:[1,0]
	v_pk_mul_f32 v[62:63], v[62:63], v[186:187] op_sel_hi:[1,0]
	v_pk_mul_f32 v[56:57], v[56:57], v[186:187] op_sel_hi:[1,0]
	v_pk_mul_f32 v[58:59], v[58:59], v[186:187] op_sel_hi:[1,0]
	v_cvt_pk_bf16_f32 v198, v60, v61
	v_cvt_pk_bf16_f32 v199, v62, v63
	v_cvt_pk_bf16_f32 v200, v56, v57
	v_cvt_pk_bf16_f32 v201, v58, v59
	global_store_dwordx4 v207, v[198:201], s[10:11]
	v_pk_mul_f32 v[52:53], v[52:53], v[186:187] op_sel_hi:[1,0]
	v_pk_mul_f32 v[54:55], v[54:55], v[186:187] op_sel_hi:[1,0]
	v_pk_mul_f32 v[48:49], v[48:49], v[186:187] op_sel_hi:[1,0]
	v_pk_mul_f32 v[50:51], v[50:51], v[186:187] op_sel_hi:[1,0]
	v_cvt_pk_bf16_f32 v202, v52, v53
	v_cvt_pk_bf16_f32 v203, v54, v55
	v_cvt_pk_bf16_f32 v204, v48, v49
	v_cvt_pk_bf16_f32 v205, v50, v51
	global_store_dwordx4 v207, v[202:205], s[10:11] offset:256
	v_add_u32_e32 v207, 0x8000, v207
	s_waitcnt vmcnt(12)
	v_pk_add_f32 v[166:167], v[166:167], v[168:169]
	s_nop 0
	v_add_f32_e32 v214, v166, v167
	v_mov_b32_e32 v215, v214
	s_nop 1
	v_permlane16_swap_b32_e32 v214, v215
	s_nop 0
	v_add_f32_e32 v214, v214, v215
	v_mov_b32_e32 v215, v214
	s_nop 1
	v_permlane32_swap_b32_e32 v214, v215
	s_nop 0
	v_add_f32_e32 v214, v214, v215
	v_fmamk_f32 v214, v214, 0x3a800000, v248
	v_rsq_f32_e32 v188, v214
	s_nop 0
	v_pk_mul_f32 v[44:45], v[44:45], v[188:189] op_sel_hi:[1,0]
	v_pk_mul_f32 v[46:47], v[46:47], v[188:189] op_sel_hi:[1,0]
	v_pk_mul_f32 v[40:41], v[40:41], v[188:189] op_sel_hi:[1,0]
	v_pk_mul_f32 v[42:43], v[42:43], v[188:189] op_sel_hi:[1,0]
	v_cvt_pk_bf16_f32 v198, v44, v45
	v_cvt_pk_bf16_f32 v199, v46, v47
	v_cvt_pk_bf16_f32 v200, v40, v41
	v_cvt_pk_bf16_f32 v201, v42, v43
	global_store_dwordx4 v207, v[198:201], s[10:11]
	v_pk_mul_f32 v[36:37], v[36:37], v[188:189] op_sel_hi:[1,0]
	v_pk_mul_f32 v[38:39], v[38:39], v[188:189] op_sel_hi:[1,0]
	v_pk_mul_f32 v[32:33], v[32:33], v[188:189] op_sel_hi:[1,0]
	v_pk_mul_f32 v[34:35], v[34:35], v[188:189] op_sel_hi:[1,0]
	v_cvt_pk_bf16_f32 v202, v36, v37
	v_cvt_pk_bf16_f32 v203, v38, v39
	v_cvt_pk_bf16_f32 v204, v32, v33
	v_cvt_pk_bf16_f32 v205, v34, v35
	global_store_dwordx4 v207, v[202:205], s[10:11] offset:256
	v_add_u32_e32 v207, 0x8000, v207
	s_waitcnt vmcnt(13)
	v_pk_add_f32 v[170:171], v[170:171], v[172:173]
	s_nop 0
	v_add_f32_e32 v214, v170, v171
	v_mov_b32_e32 v215, v214
	s_nop 1
	v_permlane16_swap_b32_e32 v214, v215
	s_nop 0
	v_add_f32_e32 v214, v214, v215
	v_mov_b32_e32 v215, v214
	s_nop 1
	v_permlane32_swap_b32_e32 v214, v215
	s_nop 0
	v_add_f32_e32 v214, v214, v215
	v_fmamk_f32 v214, v214, 0x3a800000, v248
	v_rsq_f32_e32 v190, v214
	s_nop 0
	v_pk_mul_f32 v[28:29], v[28:29], v[190:191] op_sel_hi:[1,0]
	v_pk_mul_f32 v[30:31], v[30:31], v[190:191] op_sel_hi:[1,0]
	v_pk_mul_f32 v[24:25], v[24:25], v[190:191] op_sel_hi:[1,0]
	v_pk_mul_f32 v[26:27], v[26:27], v[190:191] op_sel_hi:[1,0]
	v_cvt_pk_bf16_f32 v198, v28, v29
	v_cvt_pk_bf16_f32 v199, v30, v31
	v_cvt_pk_bf16_f32 v200, v24, v25
	v_cvt_pk_bf16_f32 v201, v26, v27
	global_store_dwordx4 v207, v[198:201], s[10:11]
	v_pk_mul_f32 v[20:21], v[20:21], v[190:191] op_sel_hi:[1,0]
	v_pk_mul_f32 v[22:23], v[22:23], v[190:191] op_sel_hi:[1,0]
	v_pk_mul_f32 v[16:17], v[16:17], v[190:191] op_sel_hi:[1,0]
	v_pk_mul_f32 v[18:19], v[18:19], v[190:191] op_sel_hi:[1,0]
	v_cvt_pk_bf16_f32 v202, v20, v21
	v_cvt_pk_bf16_f32 v203, v22, v23
	v_cvt_pk_bf16_f32 v204, v16, v17
	v_cvt_pk_bf16_f32 v205, v18, v19
	global_store_dwordx4 v207, v[202:205], s[10:11] offset:256
	v_add_u32_e32 v207, 0x8000, v207
	s_waitcnt vmcnt(14)
	v_pk_add_f32 v[174:175], v[174:175], v[176:177]
	s_nop 0
	v_add_f32_e32 v214, v174, v175
	v_mov_b32_e32 v215, v214
	s_nop 1
	v_permlane16_swap_b32_e32 v214, v215
	s_nop 0
	v_add_f32_e32 v214, v214, v215
	v_mov_b32_e32 v215, v214
	s_nop 1
	v_permlane32_swap_b32_e32 v214, v215
	s_nop 0
	v_add_f32_e32 v214, v214, v215
	v_fmamk_f32 v214, v214, 0x3a800000, v248
	v_rsq_f32_e32 v192, v214
	s_nop 0
	v_pk_mul_f32 v[12:13], v[12:13], v[192:193] op_sel_hi:[1,0]
	v_pk_mul_f32 v[14:15], v[14:15], v[192:193] op_sel_hi:[1,0]
	v_pk_mul_f32 v[8:9], v[8:9], v[192:193] op_sel_hi:[1,0]
	v_pk_mul_f32 v[10:11], v[10:11], v[192:193] op_sel_hi:[1,0]
	v_cvt_pk_bf16_f32 v198, v12, v13
	v_cvt_pk_bf16_f32 v199, v14, v15
	v_cvt_pk_bf16_f32 v200, v8, v9
	v_cvt_pk_bf16_f32 v201, v10, v11
	global_store_dwordx4 v207, v[198:201], s[10:11]
	v_pk_mul_f32 v[4:5], v[4:5], v[192:193] op_sel_hi:[1,0]
	v_pk_mul_f32 v[6:7], v[6:7], v[192:193] op_sel_hi:[1,0]
	v_pk_mul_f32 v[0:1], v[0:1], v[192:193] op_sel_hi:[1,0]
	v_pk_mul_f32 v[2:3], v[2:3], v[192:193] op_sel_hi:[1,0]
	v_cvt_pk_bf16_f32 v202, v4, v5
	v_cvt_pk_bf16_f32 v203, v6, v7
	v_cvt_pk_bf16_f32 v204, v0, v1
	v_cvt_pk_bf16_f32 v205, v2, v3
	global_store_dwordx4 v207, v[202:205], s[10:11] offset:256
	s_and_b64 vcc, exec, s[4:5]
	s_cbranch_vccz .LBB0_816
	s_waitcnt vmcnt(0)
	s_cmpk_gt_u32 s30, 0xff
	s_cbranch_scc1 .LBB0_827
	s_barrier

.LBB0_921:
	s_add_u32 s8, s6, 0xfffe0080
	s_addc_u32 s9, s7, -1
	s_add_i32 s84, 0, 0x10000
	v_add_u32_e32 v140, s84, v253
	ds_read_b128 v[128:131], v140
	ds_read_b128 v[132:135], v140 offset:1024
	ds_read_b128 v[136:139], v140 offset:2048
	ds_read_b128 v[140:143], v140 offset:3072
	s_cmp_eq_u32 s73, 12
	s_cselect_b32 s11, s15, s9
	s_cselect_b32 s10, s39, s8
	s_cselect_b32 s9, s65, vcc_hi
	s_cselect_b32 s8, s67, vcc_lo
	v_lshl_add_u64 v[176:177], s[6:7], 0, v[220:221]
	s_add_i32 m0, s46, 0xc000
	ds_read_b128 v[144:147], v251
	ds_read_b128 v[148:151], v251 offset:1024
	ds_read_b128 v[152:155], v251 offset:2048
	ds_read_b128 v[156:159], v251 offset:3072
	ds_read_b128 v[160:163], v251 offset:4096
	ds_read_b128 v[164:167], v251 offset:5120
	ds_read_b128 v[168:171], v251 offset:6144
	ds_read_b128 v[172:175], v251 offset:7168
	global_load_lds_dwordx4 v[176:177], off
	v_lshl_add_u64 v[176:177], s[6:7], 0, v[222:223]
	s_add_i32 m0, s46, 0xe000
	s_nop 0
	global_load_lds_dwordx4 v[176:177], off
	s_waitcnt lgkmcnt(8)
	s_barrier
	s_waitcnt lgkmcnt(0)
	s_setprio 1
	s_waitcnt lgkmcnt(0)
	v_mfma_f32_16x16x32_bf16 v[124:127], v[128:131], v[144:147], v[124:127]
	v_mfma_f32_16x16x32_bf16 v[120:123], v[136:139], v[144:147], v[120:123]
	v_mfma_f32_16x16x32_bf16 v[92:95], v[128:131], v[152:155], v[92:95]
	v_mfma_f32_16x16x32_bf16 v[44:47], v[136:139], v[152:155], v[44:47]
	v_mfma_f32_16x16x32_bf16 v[84:87], v[128:131], v[160:163], v[84:87]
	v_mfma_f32_16x16x32_bf16 v[40:43], v[136:139], v[160:163], v[40:43]
	v_mfma_f32_16x16x32_bf16 v[76:79], v[128:131], v[168:171], v[76:79]
	v_mfma_f32_16x16x32_bf16 v[36:39], v[136:139], v[168:171], v[36:39]
	v_mfma_f32_16x16x32_bf16 v[124:127], v[132:135], v[148:151], v[124:127]
	v_mfma_f32_16x16x32_bf16 v[120:123], v[140:143], v[148:151], v[120:123]
	v_mfma_f32_16x16x32_bf16 v[92:95], v[132:135], v[156:159], v[92:95]
	v_mfma_f32_16x16x32_bf16 v[44:47], v[140:143], v[156:159], v[44:47]
	v_mfma_f32_16x16x32_bf16 v[84:87], v[132:135], v[164:167], v[84:87]
	v_mfma_f32_16x16x32_bf16 v[40:43], v[140:143], v[164:167], v[40:43]
	v_mfma_f32_16x16x32_bf16 v[76:79], v[132:135], v[172:175], v[76:79]
	v_mfma_f32_16x16x32_bf16 v[36:39], v[140:143], v[172:175], v[36:39]
	s_setprio 0
	s_barrier
	s_add_i32 s86, 0, 0x14000
	s_add_i32 s84, s84, s88
	v_add_u32_e32 v188, s86, v253
	v_lshl_add_u64 v[192:193], s[8:9], 0, v[208:209]
	s_mov_b32 m0, s84
	ds_read_b128 v[176:179], v188
	ds_read_b128 v[180:183], v188 offset:1024
	ds_read_b128 v[184:187], v188 offset:2048
	ds_read_b128 v[188:191], v188 offset:3072
	global_load_lds_dwordx4 v[192:193], off
	v_lshl_add_u64 v[194:195], s[8:9], 0, v[214:215]
	s_add_i32 m0, s84, 0x2000
	s_nop 0
	global_load_lds_dwordx4 v[194:195], off
	s_barrier
	s_waitcnt lgkmcnt(0)
	s_setprio 1
	s_waitcnt lgkmcnt(0)
	v_mfma_f32_16x16x32_bf16 v[116:119], v[176:179], v[144:147], v[116:119]
	v_mfma_f32_16x16x32_bf16 v[112:115], v[184:187], v[144:147], v[112:115]
	v_mfma_f32_16x16x32_bf16 v[88:91], v[176:179], v[152:155], v[88:91]
	v_mfma_f32_16x16x32_bf16 v[32:35], v[184:187], v[152:155], v[32:35]
	v_mfma_f32_16x16x32_bf16 v[80:83], v[176:179], v[160:163], v[80:83]
	v_mfma_f32_16x16x32_bf16 v[28:31], v[184:187], v[160:163], v[28:31]
	v_mfma_f32_16x16x32_bf16 v[72:75], v[176:179], v[168:171], v[72:75]
	v_mfma_f32_16x16x32_bf16 v[24:27], v[184:187], v[168:171], v[24:27]
	v_mfma_f32_16x16x32_bf16 v[116:119], v[180:183], v[148:151], v[116:119]
	v_mfma_f32_16x16x32_bf16 v[112:115], v[188:191], v[148:151], v[112:115]
	v_mfma_f32_16x16x32_bf16 v[88:91], v[180:183], v[156:159], v[88:91]
	v_mfma_f32_16x16x32_bf16 v[32:35], v[188:191], v[156:159], v[32:35]
	v_mfma_f32_16x16x32_bf16 v[80:83], v[180:183], v[164:167], v[80:83]
	v_mfma_f32_16x16x32_bf16 v[28:31], v[188:191], v[164:167], v[28:31]
	v_mfma_f32_16x16x32_bf16 v[72:75], v[180:183], v[172:175], v[72:75]
	v_mfma_f32_16x16x32_bf16 v[24:27], v[188:191], v[172:175], v[24:27]
	s_setprio 0
	s_mov_b32 m0, s46
	v_lshl_add_u64 v[196:197], s[10:11], 0, v[218:219]
	s_barrier
	ds_read_b128 v[144:147], v251 offset:16384
	ds_read_b128 v[148:151], v251 offset:17408
	ds_read_b128 v[152:155], v251 offset:18432
	ds_read_b128 v[156:159], v251 offset:19456
	ds_read_b128 v[160:163], v251 offset:20480
	ds_read_b128 v[164:167], v251 offset:21504
	ds_read_b128 v[168:171], v251 offset:22528
	ds_read_b128 v[172:175], v251 offset:23552
	global_load_lds_dwordx4 v[196:197], off
	v_lshl_add_u64 v[198:199], s[10:11], 0, v[216:217]
	s_mov_b32 m0, s50
	s_nop 0
	global_load_lds_dwordx4 v[198:199], off
	s_barrier
	s_waitcnt lgkmcnt(0)
	s_setprio 1
	s_waitcnt lgkmcnt(0)
	v_mfma_f32_16x16x32_bf16 v[68:71], v[128:131], v[144:147], v[68:71]
	v_mfma_f32_16x16x32_bf16 v[20:23], v[136:139], v[144:147], v[20:23]
	v_mfma_f32_16x16x32_bf16 v[64:67], v[128:131], v[152:155], v[64:67]
	v_mfma_f32_16x16x32_bf16 v[16:19], v[136:139], v[152:155], v[16:19]
	v_mfma_f32_16x16x32_bf16 v[60:63], v[128:131], v[160:163], v[60:63]
	v_mfma_f32_16x16x32_bf16 v[12:15], v[136:139], v[160:163], v[12:15]
	v_mfma_f32_16x16x32_bf16 v[108:111], v[128:131], v[168:171], v[108:111]
	v_mfma_f32_16x16x32_bf16 v[104:107], v[136:139], v[168:171], v[104:107]
	v_mfma_f32_16x16x32_bf16 v[68:71], v[132:135], v[148:151], v[68:71]
	v_mfma_f32_16x16x32_bf16 v[20:23], v[140:143], v[148:151], v[20:23]
	v_mfma_f32_16x16x32_bf16 v[64:67], v[132:135], v[156:159], v[64:67]
	v_mfma_f32_16x16x32_bf16 v[16:19], v[140:143], v[156:159], v[16:19]
	v_mfma_f32_16x16x32_bf16 v[60:63], v[132:135], v[164:167], v[60:63]
	v_mfma_f32_16x16x32_bf16 v[12:15], v[140:143], v[164:167], v[12:15]
	v_mfma_f32_16x16x32_bf16 v[108:111], v[132:135], v[172:175], v[108:111]
	v_mfma_f32_16x16x32_bf16 v[104:107], v[140:143], v[172:175], v[104:107]
	s_setprio 0
	s_barrier
	s_add_u32 s84, s8, 0x40000
	s_addc_u32 s85, s9, 0
	s_add_i32 s86, s86, s88
	v_lshl_add_u64 v[128:129], s[84:85], 0, v[208:209]
	s_mov_b32 m0, s86
	s_nop 0
	global_load_lds_dwordx4 v[128:129], off
	v_lshl_add_u64 v[128:129], s[84:85], 0, v[214:215]
	s_add_i32 m0, s86, 0x2000
	s_nop 0
	global_load_lds_dwordx4 v[128:129], off
	s_waitcnt vmcnt(6)
	s_barrier
	s_setprio 1
	v_mfma_f32_16x16x32_bf16 v[56:59], v[176:179], v[144:147], v[56:59]
	v_mfma_f32_16x16x32_bf16 v[8:11], v[184:187], v[144:147], v[8:11]
	v_mfma_f32_16x16x32_bf16 v[52:55], v[176:179], v[152:155], v[52:55]
	v_mfma_f32_16x16x32_bf16 v[4:7], v[184:187], v[152:155], v[4:7]
	v_mfma_f32_16x16x32_bf16 v[48:51], v[176:179], v[160:163], v[48:51]
	v_mfma_f32_16x16x32_bf16 v[0:3], v[184:187], v[160:163], v[0:3]
	v_mfma_f32_16x16x32_bf16 v[100:103], v[176:179], v[168:171], v[100:103]
	v_mfma_f32_16x16x32_bf16 v[96:99], v[184:187], v[168:171], v[96:99]
	v_mfma_f32_16x16x32_bf16 v[56:59], v[180:183], v[148:151], v[56:59]
	v_mfma_f32_16x16x32_bf16 v[8:11], v[188:191], v[148:151], v[8:11]
	v_mfma_f32_16x16x32_bf16 v[52:55], v[180:183], v[156:159], v[52:55]
	v_mfma_f32_16x16x32_bf16 v[4:7], v[188:191], v[156:159], v[4:7]
	v_mfma_f32_16x16x32_bf16 v[48:51], v[180:183], v[164:167], v[48:51]
	v_mfma_f32_16x16x32_bf16 v[0:3], v[188:191], v[164:167], v[0:3]
	v_mfma_f32_16x16x32_bf16 v[100:103], v[180:183], v[172:175], v[100:103]
	v_mfma_f32_16x16x32_bf16 v[96:99], v[188:191], v[172:175], v[96:99]
	s_setprio 0
	s_add_i32 s84, 0, 0x18000
	v_add_u32_e32 v140, s84, v253
	s_barrier
	ds_read_b128 v[128:131], v140
	ds_read_b128 v[132:135], v140 offset:1024
	ds_read_b128 v[136:139], v140 offset:2048
	ds_read_b128 v[140:143], v140 offset:3072
	s_add_u32 s10, s10, 0x20000
	s_addc_u32 s11, s11, 0
	s_mov_b32 m0, s51
	v_lshl_add_u64 v[176:177], s[10:11], 0, v[218:219]
	ds_read_b128 v[144:147], v251 offset:32768
	ds_read_b128 v[148:151], v251 offset:33792
	ds_read_b128 v[152:155], v251 offset:34816
	ds_read_b128 v[156:159], v251 offset:35840
	ds_read_b128 v[160:163], v251 offset:36864
	ds_read_b128 v[164:167], v251 offset:37888
	ds_read_b128 v[168:171], v251 offset:38912
	ds_read_b128 v[172:175], v251 offset:39936
	global_load_lds_dwordx4 v[176:177], off
	v_lshl_add_u64 v[176:177], s[10:11], 0, v[216:217]
	s_mov_b32 m0, s34
	s_nop 0
	global_load_lds_dwordx4 v[176:177], off
	s_waitcnt lgkmcnt(8)
	s_barrier
	s_waitcnt lgkmcnt(0)
	s_setprio 1
	s_waitcnt lgkmcnt(0)
	v_mfma_f32_16x16x32_bf16 v[124:127], v[128:131], v[144:147], v[124:127]
	v_mfma_f32_16x16x32_bf16 v[120:123], v[136:139], v[144:147], v[120:123]
	v_mfma_f32_16x16x32_bf16 v[92:95], v[128:131], v[152:155], v[92:95]
	v_mfma_f32_16x16x32_bf16 v[44:47], v[136:139], v[152:155], v[44:47]
	v_mfma_f32_16x16x32_bf16 v[84:87], v[128:131], v[160:163], v[84:87]
	v_mfma_f32_16x16x32_bf16 v[40:43], v[136:139], v[160:163], v[40:43]
	v_mfma_f32_16x16x32_bf16 v[76:79], v[128:131], v[168:171], v[76:79]
	v_mfma_f32_16x16x32_bf16 v[36:39], v[136:139], v[168:171], v[36:39]
	v_mfma_f32_16x16x32_bf16 v[124:127], v[132:135], v[148:151], v[124:127]
	v_mfma_f32_16x16x32_bf16 v[120:123], v[140:143], v[148:151], v[120:123]
	v_mfma_f32_16x16x32_bf16 v[92:95], v[132:135], v[156:159], v[92:95]
	v_mfma_f32_16x16x32_bf16 v[44:47], v[140:143], v[156:159], v[44:47]
	v_mfma_f32_16x16x32_bf16 v[84:87], v[132:135], v[164:167], v[84:87]
	v_mfma_f32_16x16x32_bf16 v[40:43], v[140:143], v[164:167], v[40:43]
	v_mfma_f32_16x16x32_bf16 v[76:79], v[132:135], v[172:175], v[76:79]
	v_mfma_f32_16x16x32_bf16 v[36:39], v[140:143], v[172:175], v[36:39]
	s_setprio 0
	s_barrier
	s_add_i32 s10, 0, 0x1c000
	s_add_i32 s11, s84, s88
	v_add_u32_e32 v188, s10, v253
	v_lshl_add_u64 v[192:193], v[192:193], 0, s[40:41]
	s_mov_b32 m0, s11
	ds_read_b128 v[176:179], v188
	ds_read_b128 v[180:183], v188 offset:1024
	ds_read_b128 v[184:187], v188 offset:2048
	ds_read_b128 v[188:191], v188 offset:3072
	global_load_lds_dwordx4 v[192:193], off
	v_lshl_add_u64 v[192:193], v[194:195], 0, s[40:41]
	s_add_i32 m0, s11, 0x2000
	s_nop 0
	global_load_lds_dwordx4 v[192:193], off
	s_barrier
	s_waitcnt lgkmcnt(0)
	s_setprio 1
	s_waitcnt lgkmcnt(0)
	v_mfma_f32_16x16x32_bf16 v[116:119], v[176:179], v[144:147], v[116:119]
	v_mfma_f32_16x16x32_bf16 v[112:115], v[184:187], v[144:147], v[112:115]
	v_mfma_f32_16x16x32_bf16 v[88:91], v[176:179], v[152:155], v[88:91]
	v_mfma_f32_16x16x32_bf16 v[32:35], v[184:187], v[152:155], v[32:35]
	v_mfma_f32_16x16x32_bf16 v[80:83], v[176:179], v[160:163], v[80:83]
	v_mfma_f32_16x16x32_bf16 v[28:31], v[184:187], v[160:163], v[28:31]
	v_mfma_f32_16x16x32_bf16 v[72:75], v[176:179], v[168:171], v[72:75]
	v_mfma_f32_16x16x32_bf16 v[24:27], v[184:187], v[168:171], v[24:27]
	v_mfma_f32_16x16x32_bf16 v[116:119], v[180:183], v[148:151], v[116:119]
	v_mfma_f32_16x16x32_bf16 v[112:115], v[188:191], v[148:151], v[112:115]
	v_mfma_f32_16x16x32_bf16 v[88:91], v[180:183], v[156:159], v[88:91]
	v_mfma_f32_16x16x32_bf16 v[32:35], v[188:191], v[156:159], v[32:35]
	v_mfma_f32_16x16x32_bf16 v[80:83], v[180:183], v[164:167], v[80:83]
	v_mfma_f32_16x16x32_bf16 v[28:31], v[188:191], v[164:167], v[28:31]
	v_mfma_f32_16x16x32_bf16 v[72:75], v[180:183], v[172:175], v[72:75]
	v_mfma_f32_16x16x32_bf16 v[24:27], v[188:191], v[172:175], v[24:27]
	s_setprio 0
	s_mov_b32 m0, s92
	v_lshl_add_u64 v[192:193], v[196:197], 0, s[40:41]
	s_barrier
	ds_read_b128 v[144:147], v251 offset:49152
	ds_read_b128 v[148:151], v251 offset:50176
	ds_read_b128 v[152:155], v251 offset:51200
	ds_read_b128 v[156:159], v251 offset:52224
	ds_read_b128 v[160:163], v251 offset:53248
	ds_read_b128 v[164:167], v251 offset:54272
	ds_read_b128 v[168:171], v251 offset:55296
	ds_read_b128 v[172:175], v251 offset:56320
	global_load_lds_dwordx4 v[192:193], off
	v_lshl_add_u64 v[192:193], v[198:199], 0, s[40:41]
	s_mov_b32 m0, s93
	s_nop 0
	global_load_lds_dwordx4 v[192:193], off
	s_barrier
	s_waitcnt lgkmcnt(0)
	s_setprio 1
	s_waitcnt lgkmcnt(0)
	v_mfma_f32_16x16x32_bf16 v[68:71], v[128:131], v[144:147], v[68:71]
	v_mfma_f32_16x16x32_bf16 v[20:23], v[136:139], v[144:147], v[20:23]
	v_mfma_f32_16x16x32_bf16 v[64:67], v[128:131], v[152:155], v[64:67]
	v_mfma_f32_16x16x32_bf16 v[16:19], v[136:139], v[152:155], v[16:19]
	v_mfma_f32_16x16x32_bf16 v[60:63], v[128:131], v[160:163], v[60:63]
	v_mfma_f32_16x16x32_bf16 v[12:15], v[136:139], v[160:163], v[12:15]
	v_mfma_f32_16x16x32_bf16 v[108:111], v[128:131], v[168:171], v[108:111]
	v_mfma_f32_16x16x32_bf16 v[104:107], v[136:139], v[168:171], v[104:107]
	v_mfma_f32_16x16x32_bf16 v[68:71], v[132:135], v[148:151], v[68:71]
	v_mfma_f32_16x16x32_bf16 v[20:23], v[140:143], v[148:151], v[20:23]
	v_mfma_f32_16x16x32_bf16 v[64:67], v[132:135], v[156:159], v[64:67]
	v_mfma_f32_16x16x32_bf16 v[16:19], v[140:143], v[156:159], v[16:19]
	v_mfma_f32_16x16x32_bf16 v[60:63], v[132:135], v[164:167], v[60:63]
	v_mfma_f32_16x16x32_bf16 v[12:15], v[140:143], v[164:167], v[12:15]
	v_mfma_f32_16x16x32_bf16 v[108:111], v[132:135], v[172:175], v[108:111]
	v_mfma_f32_16x16x32_bf16 v[104:107], v[140:143], v[172:175], v[104:107]
	s_setprio 0
	s_barrier
	s_add_u32 s8, s8, 0x40080
	s_addc_u32 s9, s9, 0
	s_add_i32 s10, s10, s88
	v_lshl_add_u64 v[128:129], s[8:9], 0, v[208:209]
	s_mov_b32 m0, s10
	s_nop 0
	global_load_lds_dwordx4 v[128:129], off
	v_lshl_add_u64 v[128:129], s[8:9], 0, v[214:215]
	s_add_i32 m0, s10, 0x2000
	s_nop 0
	global_load_lds_dwordx4 v[128:129], off
	s_waitcnt vmcnt(6)
	s_barrier
	s_setprio 1
	v_mfma_f32_16x16x32_bf16 v[56:59], v[176:179], v[144:147], v[56:59]
	v_mfma_f32_16x16x32_bf16 v[8:11], v[184:187], v[144:147], v[8:11]
	v_mfma_f32_16x16x32_bf16 v[52:55], v[176:179], v[152:155], v[52:55]
	v_mfma_f32_16x16x32_bf16 v[4:7], v[184:187], v[152:155], v[4:7]
	v_mfma_f32_16x16x32_bf16 v[48:51], v[176:179], v[160:163], v[48:51]
	v_mfma_f32_16x16x32_bf16 v[0:3], v[184:187], v[160:163], v[0:3]
	v_mfma_f32_16x16x32_bf16 v[100:103], v[176:179], v[168:171], v[100:103]
	v_mfma_f32_16x16x32_bf16 v[96:99], v[184:187], v[168:171], v[96:99]
	v_mfma_f32_16x16x32_bf16 v[56:59], v[180:183], v[148:151], v[56:59]
	v_mfma_f32_16x16x32_bf16 v[8:11], v[188:191], v[148:151], v[8:11]
	v_mfma_f32_16x16x32_bf16 v[52:55], v[180:183], v[156:159], v[52:55]
	v_mfma_f32_16x16x32_bf16 v[4:7], v[188:191], v[156:159], v[4:7]
	v_mfma_f32_16x16x32_bf16 v[48:51], v[180:183], v[164:167], v[48:51]
	v_mfma_f32_16x16x32_bf16 v[0:3], v[188:191], v[164:167], v[0:3]
	v_mfma_f32_16x16x32_bf16 v[100:103], v[180:183], v[172:175], v[100:103]
	v_mfma_f32_16x16x32_bf16 v[96:99], v[188:191], v[172:175], v[96:99]
	s_setprio 0
	s_add_i32 s73, s73, 2
	s_add_u32 s6, s6, 0x100
	s_addc_u32 s7, s7, 0
	s_add_u32 vcc_lo, vcc_lo, 0x100
	s_addc_u32 vcc_hi, vcc_hi, 0
	s_cmp_gt_u32 s73, 13
	s_barrier
	s_cbranch_scc0 .LBB0_921
	s_lshl_b32 s6, s38, 8
	v_mov_b32_e32 v250, v210
	v_mov_b32_e32 v254, v249
	s_add_i32 s6, s6, s90
	v_mov_b64_e32 v[242:243], s[44:45]
	v_add_u32_e32 v234, s6, v254
	v_ashrrev_i32_e32 v235, 31, v234
	v_mbcnt_lo_u32_b32 v212, -1, 0
	v_mbcnt_hi_u32_b32 v212, -1, v212
	v_lshlrev_b32_e32 v244, 6, v234
	v_and_b32_e32 v212, 48, v212
	v_add_u32_e32 v212, v244, v212
	v_add_u32_e32 v213, 0x1000, v212
	v_add_u32_e32 v245, 0x1000, v244
	global_load_dwordx4 v[192:195], v212, s[20:21]
	global_load_dwordx4 v[196:199], v212, s[20:21] offset:1024
	global_load_dwordx4 v[200:203], v213, s[20:21] offset:2048
	global_load_dwordx4 v[204:207], v213, s[20:21] offset:3072
	global_load_dwordx4 v[160:163], v244, s[20:21] offset:2096
	global_load_dwordx4 v[164:167], v244, s[20:21] offset:2080
	global_load_dwordx4 v[176:179], v244, s[20:21] offset:2064
	global_load_dwordx4 v[180:183], v244, s[20:21] offset:2048
	global_load_dwordx4 v[168:171], v244, s[20:21] offset:3120
	global_load_dwordx4 v[172:175], v244, s[20:21] offset:3104
	global_load_dwordx4 v[184:187], v244, s[20:21] offset:3088
	global_load_dwordx4 v[188:191], v244, s[20:21] offset:3072
	global_load_dwordx4 v[144:147], v245, s[20:21] offset:48
	global_load_dwordx4 v[148:151], v245, s[20:21] offset:32
	global_load_dwordx4 v[152:155], v245, s[20:21] offset:16
	global_load_dwordx4 v[156:159], v245, s[20:21]
	global_load_dwordx4 v[128:131], v245, s[20:21] offset:1072
	global_load_dwordx4 v[132:135], v245, s[20:21] offset:1056
	global_load_dwordx4 v[136:139], v245, s[20:21] offset:1040
	global_load_dwordx4 v[140:143], v245, s[20:21] offset:1024
	v_add_u32_e32 v236, 16, v234
	v_ashrrev_i32_e32 v237, 31, v236
	v_add_u32_e32 v238, 32, v234
	v_ashrrev_i32_e32 v239, 31, v238
	v_add_u32_e32 v232, 48, v234
	v_ashrrev_i32_e32 v233, 31, v232
	v_add_u32_e32 v230, 64, v234
	v_ashrrev_i32_e32 v231, 31, v230
	v_add_u32_e32 v228, 0x50, v234
	v_ashrrev_i32_e32 v229, 31, v228
	v_add_u32_e32 v224, 0x60, v234
	v_ashrrev_i32_e32 v225, 31, v224
	v_add_u32_e32 v226, 0x70, v234
	v_ashrrev_i32_e32 v227, 31, v226
	s_lshl_b32 s14, s14, 7
	s_or_b32 s14, s14, s35
	s_waitcnt vmcnt(16)
	v_pk_add_f32 v[192:193], v[192:193], v[194:195]
	s_nop 0
	v_add_f32_e32 v246, v192, v193
	v_mov_b32_e32 v247, v246
	s_nop 1
	v_permlane16_swap_b32_e32 v246, v247
	s_nop 0
	v_add_f32_e32 v246, v246, v247
	v_mov_b32_e32 v247, v246
	s_nop 1
	v_permlane32_swap_b32_e32 v246, v247
	s_nop 0
	v_add_f32_e32 v193, v246, v247
	v_pk_add_f32 v[196:197], v[196:197], v[198:199]
	s_nop 0
	v_add_f32_e32 v246, v196, v197
	v_mov_b32_e32 v247, v246
	s_nop 1
	v_permlane16_swap_b32_e32 v246, v247
	s_nop 0
	v_add_f32_e32 v246, v246, v247
	v_mov_b32_e32 v247, v246
	s_nop 1
	v_permlane32_swap_b32_e32 v246, v247
	s_nop 0
	v_add_f32_e32 v192, v246, v247
	v_pk_add_f32 v[200:201], v[200:201], v[202:203]
	s_nop 0
	v_add_f32_e32 v246, v200, v201
	v_mov_b32_e32 v247, v246
	s_nop 1
	v_permlane16_swap_b32_e32 v246, v247
	s_nop 0
	v_add_f32_e32 v246, v246, v247
	v_mov_b32_e32 v247, v246
	s_nop 1
	v_permlane32_swap_b32_e32 v246, v247
	s_nop 0
	v_add_f32_e32 v197, v246, v247
	v_pk_add_f32 v[204:205], v[204:205], v[206:207]
	s_nop 0
	v_add_f32_e32 v246, v204, v205
	v_mov_b32_e32 v247, v246
	s_nop 1
	v_permlane16_swap_b32_e32 v246, v247
	s_nop 0
	v_add_f32_e32 v246, v246, v247
	v_mov_b32_e32 v247, v246
	s_nop 1
	v_permlane32_swap_b32_e32 v246, v247
	s_nop 0
	v_add_f32_e32 v196, v246, v247
	s_nop 0
	v_pk_fma_f32 v[240:241], v[192:193], s[42:43], v[242:243] op_sel_hi:[1,0,0]
	v_pk_fma_f32 v[202:203], v[196:197], s[42:43], v[242:243] op_sel_hi:[1,0,0]
	v_cmp_gt_f32_e64 s[6:7], s97, v240
	v_cmp_gt_f32_e32 vcc, s97, v241
	s_waitcnt vmcnt(0)
	v_lshl_add_u32 v192, v250, 3, s14
	v_add_u32_e32 v193, -14, v254
	v_cmp_gt_f32_e64 s[8:9], s97, v203
	v_cmp_gt_f32_e64 s[10:11], s97, v202
	v_cmp_lt_u32_e64 s[14:15], -13, v193
	v_ashrrev_i32_e32 v193, 31, v192
	s_and_saveexec_b64 s[86:87], s[14:15]
	s_xor_b64 s[14:15], exec, s[86:87]
	s_or_saveexec_b64 s[14:15], s[14:15]
	v_mul_f32_e32 v194, 0x4b800000, v241
	v_cndmask_b32_e32 v194, v241, v194, vcc
	v_rsq_f32_e32 v194, v194
	s_nop 0
	v_mul_f32_e32 v195, 0x45800000, v194
	v_cndmask_b32_e32 v204, v194, v195, vcc
	v_pk_mul_f32 v[196:197], v[118:119], v[204:205] op_sel_hi:[1,0]
	v_mul_f32_e32 v118, 0x4b800000, v202
	v_cndmask_b32_e64 v118, v202, v118, s[10:11]
	v_rsq_f32_e32 v118, v118
	v_pk_mul_f32 v[200:201], v[116:117], v[204:205] op_sel_hi:[1,0]
	v_pk_mul_f32 v[194:195], v[126:127], v[204:205] op_sel_hi:[1,0]
	v_pk_mul_f32 v[198:199], v[124:125], v[204:205] op_sel_hi:[1,0]
	v_mul_f32_e32 v116, 0x45800000, v118
	v_cndmask_b32_e64 v116, v118, v116, s[10:11]
	v_pk_mul_f32 v[122:123], v[122:123], v[204:205] op_sel_hi:[1,0]
	v_pk_mul_f32 v[120:121], v[120:121], v[204:205] op_sel_hi:[1,0]
	v_pk_mul_f32 v[114:115], v[114:115], v[204:205] op_sel_hi:[1,0]
	v_pk_mul_f32 v[112:113], v[112:113], v[204:205] op_sel_hi:[1,0]
	v_pk_mul_f32 v[110:111], v[110:111], v[116:117] op_sel_hi:[1,0]
	v_pk_mul_f32 v[108:109], v[108:109], v[116:117] op_sel_hi:[1,0]
	v_pk_mul_f32 v[106:107], v[106:107], v[116:117] op_sel_hi:[1,0]
	v_pk_mul_f32 v[104:105], v[104:105], v[116:117] op_sel_hi:[1,0]
	v_pk_mul_f32 v[102:103], v[102:103], v[116:117] op_sel_hi:[1,0]
	v_pk_mul_f32 v[100:101], v[100:101], v[116:117] op_sel_hi:[1,0]
	v_pk_mul_f32 v[98:99], v[98:99], v[116:117] op_sel_hi:[1,0]
	v_pk_mul_f32 v[96:97], v[96:97], v[116:117] op_sel_hi:[1,0]
	s_xor_b64 exec, exec, s[14:15]
	s_cbranch_execz .LBB0_917
	v_add_u32_e32 v116, -12, v254
	v_cmp_gt_i32_e64 s[10:11], 2, v254
	s_lshl_b32 s38, s38, 3
	s_add_i32 s38, s38, s91
	v_cndmask_b32_e64 v116, v116, v254, s[10:11]
	v_add_u32_e32 v126, s38, v116
	v_mov_b64_e32 v[124:125], s[22:23]
	s_movk_i32 s38, 0x5800
	v_mad_i64_i32 v[124:125], s[38:39], v126, s38, v[124:125]
	v_cndmask_b32_e64 v119, v111, v195, s[10:11]
	v_cndmask_b32_e64 v118, v110, v194, s[10:11]
	v_cndmask_b32_e64 v117, v109, v199, s[10:11]
	v_cndmask_b32_e64 v116, v108, v198, s[10:11]
	v_lshl_add_u64 v[124:125], v[192:193], 2, v[124:125]
	s_mov_b64 s[38:39], 0x2c00
	global_store_dwordx4 v[124:125], v[116:119], off
	v_lshl_add_u64 v[126:127], v[124:125], 0, s[38:39]
	s_movk_i32 s38, 0x2000
	v_cndmask_b32_e64 v119, v107, v123, s[10:11]
	v_cndmask_b32_e64 v118, v106, v122, s[10:11]
	v_cndmask_b32_e64 v117, v105, v121, s[10:11]
	v_cndmask_b32_e64 v116, v104, v120, s[10:11]
	global_store_dwordx4 v[124:125], v[116:119], off offset:16
	v_add_co_u32_e32 v124, vcc, s38, v124
	s_nop 0
	v_cndmask_b32_e64 v119, v103, v197, s[10:11]
	v_cndmask_b32_e64 v118, v102, v196, s[10:11]
	v_cndmask_b32_e64 v117, v101, v201, s[10:11]
	v_cndmask_b32_e64 v116, v100, v200, s[10:11]
	v_addc_co_u32_e32 v125, vcc, 0, v125, vcc
	global_store_dwordx4 v[124:125], v[116:119], off offset:3072
	s_nop 1
	v_cndmask_b32_e64 v119, v99, v115, s[10:11]
	v_cndmask_b32_e64 v118, v98, v114, s[10:11]
	v_cndmask_b32_e64 v117, v97, v113, s[10:11]
	v_cndmask_b32_e64 v116, v96, v112, s[10:11]
	global_store_dwordx4 v[126:127], v[116:119], off offset:16
	s_branch .LBB0_917
